# v7 = v6 + hand-written P6 q/k rotary epilogue (loads hoisted, packed math) + nt hint on last-use streaming loads of P9 and P14
# speedup vs baseline: 1.0099x; 1.0042x over previous
;     __device__ __forceinline__ void operator()(const f32x4 (&acc)[2][2][4][2], const Unit& u, int wr, int wc, int fr, int fq) const {
;     ...
;             const int t = (u.pn - 4) >> 2, hd = (u.pn - 4) & 3;
;             bf16_t* dst = QKVG + (size_t)t * MTOK * RW + hd * HD + cw;
;             if (t < 2) {
;                 const float sc = (t == 1) ? 0.0625f : 1.0f;
; #pragma unroll
;                 for (int ai = 0; ai < 2; ++ai)
; #pragma unroll
;                     for (int m = 0; m < 4; ++m) {
;                         const int row = row0 + ai * HALF + m * 16;
;                         const float* rp = rot + ((size_t)ptab_of(row) * 128 + cw) * 2;
;                         u32x4 w1, w2;
; #pragma unroll
;                         for (int n = 0; n < 2; ++n) {
;                             const f32x4 cs0 = *(const f32x4*)(rp + 8 * n), cs1 = *(const f32x4*)(rp + 8 * n + 4);
;                             const f32x4 x1 = acc[ai][0][m][n] * sc, x2 = acc[ai][1][m][n] * sc;
.LBB0_740:
	s_andn2_b64 vcc, exec, s[12:13]
	s_cbranch_vccnz .LBB0_742
	s_cmp_lg_u32 s25, 1
	s_cbranch_scc1 .Lrot_noscale
	s_mov_b32 s12, 0x3d800000
	s_nop 7
	s_nop 7
	v_pk_mul_f32 v[126:127], v[126:127], s[12:13] op_sel_hi:[1,0]
	v_pk_mul_f32 v[128:129], v[128:129], s[12:13] op_sel_hi:[1,0]
	v_pk_mul_f32 v[122:123], v[122:123], s[12:13] op_sel_hi:[1,0]
	v_pk_mul_f32 v[124:125], v[124:125], s[12:13] op_sel_hi:[1,0]
	v_pk_mul_f32 v[118:119], v[118:119], s[12:13] op_sel_hi:[1,0]
	v_pk_mul_f32 v[120:121], v[120:121], s[12:13] op_sel_hi:[1,0]
	v_pk_mul_f32 v[114:115], v[114:115], s[12:13] op_sel_hi:[1,0]
	v_pk_mul_f32 v[116:117], v[116:117], s[12:13] op_sel_hi:[1,0]
	v_pk_mul_f32 v[110:111], v[110:111], s[12:13] op_sel_hi:[1,0]
	v_pk_mul_f32 v[112:113], v[112:113], s[12:13] op_sel_hi:[1,0]
	v_pk_mul_f32 v[106:107], v[106:107], s[12:13] op_sel_hi:[1,0]
	v_pk_mul_f32 v[108:109], v[108:109], s[12:13] op_sel_hi:[1,0]
	v_pk_mul_f32 v[102:103], v[102:103], s[12:13] op_sel_hi:[1,0]
	v_pk_mul_f32 v[104:105], v[104:105], s[12:13] op_sel_hi:[1,0]
	v_pk_mul_f32 v[98:99], v[98:99], s[12:13] op_sel_hi:[1,0]
	v_pk_mul_f32 v[100:101], v[100:101], s[12:13] op_sel_hi:[1,0]
	v_pk_mul_f32 v[94:95], v[94:95], s[12:13] op_sel_hi:[1,0]
	v_pk_mul_f32 v[96:97], v[96:97], s[12:13] op_sel_hi:[1,0]
	v_pk_mul_f32 v[90:91], v[90:91], s[12:13] op_sel_hi:[1,0]
	v_pk_mul_f32 v[92:93], v[92:93], s[12:13] op_sel_hi:[1,0]
	v_pk_mul_f32 v[86:87], v[86:87], s[12:13] op_sel_hi:[1,0]
	v_pk_mul_f32 v[88:89], v[88:89], s[12:13] op_sel_hi:[1,0]
	v_pk_mul_f32 v[82:83], v[82:83], s[12:13] op_sel_hi:[1,0]
	v_pk_mul_f32 v[84:85], v[84:85], s[12:13] op_sel_hi:[1,0]
	v_pk_mul_f32 v[78:79], v[78:79], s[12:13] op_sel_hi:[1,0]
	v_pk_mul_f32 v[80:81], v[80:81], s[12:13] op_sel_hi:[1,0]
	v_pk_mul_f32 v[74:75], v[74:75], s[12:13] op_sel_hi:[1,0]
	v_pk_mul_f32 v[76:77], v[76:77], s[12:13] op_sel_hi:[1,0]
	v_pk_mul_f32 v[70:71], v[70:71], s[12:13] op_sel_hi:[1,0]
	v_pk_mul_f32 v[72:73], v[72:73], s[12:13] op_sel_hi:[1,0]
	v_pk_mul_f32 v[66:67], v[66:67], s[12:13] op_sel_hi:[1,0]
	v_pk_mul_f32 v[68:69], v[68:69], s[12:13] op_sel_hi:[1,0]
	v_pk_mul_f32 v[62:63], v[62:63], s[12:13] op_sel_hi:[1,0]
	v_pk_mul_f32 v[64:65], v[64:65], s[12:13] op_sel_hi:[1,0]
	v_pk_mul_f32 v[58:59], v[58:59], s[12:13] op_sel_hi:[1,0]
	v_pk_mul_f32 v[60:61], v[60:61], s[12:13] op_sel_hi:[1,0]
	v_pk_mul_f32 v[54:55], v[54:55], s[12:13] op_sel_hi:[1,0]
	v_pk_mul_f32 v[56:57], v[56:57], s[12:13] op_sel_hi:[1,0]
	v_pk_mul_f32 v[50:51], v[50:51], s[12:13] op_sel_hi:[1,0]
	v_pk_mul_f32 v[52:53], v[52:53], s[12:13] op_sel_hi:[1,0]
	v_pk_mul_f32 v[46:47], v[46:47], s[12:13] op_sel_hi:[1,0]
	v_pk_mul_f32 v[48:49], v[48:49], s[12:13] op_sel_hi:[1,0]
	v_pk_mul_f32 v[42:43], v[42:43], s[12:13] op_sel_hi:[1,0]
	v_pk_mul_f32 v[44:45], v[44:45], s[12:13] op_sel_hi:[1,0]
	v_pk_mul_f32 v[38:39], v[38:39], s[12:13] op_sel_hi:[1,0]
	v_pk_mul_f32 v[40:41], v[40:41], s[12:13] op_sel_hi:[1,0]
	v_pk_mul_f32 v[34:35], v[34:35], s[12:13] op_sel_hi:[1,0]
	v_pk_mul_f32 v[36:37], v[36:37], s[12:13] op_sel_hi:[1,0]
	v_pk_mul_f32 v[30:31], v[30:31], s[12:13] op_sel_hi:[1,0]
	v_pk_mul_f32 v[32:33], v[32:33], s[12:13] op_sel_hi:[1,0]
	v_pk_mul_f32 v[26:27], v[26:27], s[12:13] op_sel_hi:[1,0]
	v_pk_mul_f32 v[28:29], v[28:29], s[12:13] op_sel_hi:[1,0]
	v_pk_mul_f32 v[22:23], v[22:23], s[12:13] op_sel_hi:[1,0]
	v_pk_mul_f32 v[24:25], v[24:25], s[12:13] op_sel_hi:[1,0]
	v_pk_mul_f32 v[18:19], v[18:19], s[12:13] op_sel_hi:[1,0]
	v_pk_mul_f32 v[20:21], v[20:21], s[12:13] op_sel_hi:[1,0]
	v_pk_mul_f32 v[14:15], v[14:15], s[12:13] op_sel_hi:[1,0]
	v_pk_mul_f32 v[16:17], v[16:17], s[12:13] op_sel_hi:[1,0]
	v_pk_mul_f32 v[10:11], v[10:11], s[12:13] op_sel_hi:[1,0]
	v_pk_mul_f32 v[12:13], v[12:13], s[12:13] op_sel_hi:[1,0]
	v_pk_mul_f32 v[6:7], v[6:7], s[12:13] op_sel_hi:[1,0]
	v_pk_mul_f32 v[8:9], v[8:9], s[12:13] op_sel_hi:[1,0]
	v_pk_mul_f32 v[2:3], v[2:3], s[12:13] op_sel_hi:[1,0]
	v_pk_mul_f32 v[4:5], v[4:5], s[12:13] op_sel_hi:[1,0]
	.Lrot_noscale:
	v_cmp_gt_i32_e32 vcc, s65, v158
	v_and_b32_e32 v159, 0x7ff, v158
	s_nop 1
	v_cndmask_b32_e32 v159, v1, v159, vcc
	v_lshl_or_b32 v159, v159, 10, v168
	global_load_dwordx4 v[170:173], v159, s[8:9]
	global_load_dwordx4 v[174:177], v159, s[8:9] offset:16
	global_load_dwordx4 v[178:181], v159, s[8:9] offset:32
	global_load_dwordx4 v[182:185], v159, s[8:9] offset:48
	s_and_b64 s[12:13], vcc, exec
	s_cselect_b32 s98, 0x4000, 0
	s_add_u32 s98, s8, s98
	s_addc_u32 s99, s9, 0
	global_load_dwordx4 v[186:189], v159, s[98:99]
	global_load_dwordx4 v[190:193], v159, s[98:99] offset:16
	global_load_dwordx4 v[194:197], v159, s[98:99] offset:32
	global_load_dwordx4 v[198:201], v159, s[98:99] offset:48
	s_and_b64 s[12:13], vcc, exec
	s_cselect_b32 s98, 0x8000, 0
	s_add_u32 s98, s8, s98
	s_addc_u32 s99, s9, 0
	global_load_dwordx4 v[202:205], v159, s[98:99]
	global_load_dwordx4 v[206:209], v159, s[98:99] offset:16
	global_load_dwordx4 v[210:213], v159, s[98:99] offset:32
	global_load_dwordx4 v[214:217], v159, s[98:99] offset:48
	s_and_b64 s[12:13], vcc, exec
	s_cselect_b32 s98, 0xc000, 0
	s_add_u32 s98, s8, s98
	s_addc_u32 s99, s9, 0
	global_load_dwordx4 v[218:221], v159, s[98:99]
	global_load_dwordx4 v[222:225], v159, s[98:99] offset:16
	global_load_dwordx4 v[226:229], v159, s[98:99] offset:32
	global_load_dwordx4 v[230:233], v159, s[98:99] offset:48
	v_mov_b32_e32 v251, 0
	v_mov_b32_e32 v250, v158
	v_lshlrev_b64 v[250:251], 11, v[250:251]
	v_lshl_add_u64 v[250:251], v[250:251], 0, v[160:161]
	s_waitcnt vmcnt(12)
; __device__ __forceinline__ unsigned cvt_pk_bf16(float lo, float hi) { unsigned r; asm volatile("v_cvt_pk_bf16_f32 %0, %1, %2" : "=v"(r) : "v"(lo), "v"(hi)); return r; }
;     __device__ __forceinline__ void operator()(const f32x4 (&acc)[2][2][4][2], const Unit& u, int wr, int wc, int fr, int fq) const {
;     ...
;                         const int row = row0 + ai * HALF + m * 16;
;                         const float* rp = rot + ((size_t)ptab_of(row) * 128 + cw) * 2;
;                         u32x4 w1, w2;
; #pragma unroll
;                         for (int n = 0; n < 2; ++n) {
;                             const f32x4 cs0 = *(const f32x4*)(rp + 8 * n), cs1 = *(const f32x4*)(rp + 8 * n + 4);
;                             const f32x4 x1 = acc[ai][0][m][n] * sc, x2 = acc[ai][1][m][n] * sc;
;                             const float a0 = x1[0] * cs0[0] - x2[0] * cs0[1], b0 = x2[0] * cs0[0] + x1[0] * cs0[1];
;                             const float a1 = x1[1] * cs0[2] - x2[1] * cs0[3], b1 = x2[1] * cs0[2] + x1[1] * cs0[3];
;                             const float a2 = x1[2] * cs1[0] - x2[2] * cs1[1], b2 = x2[2] * cs1[0] + x1[2] * cs1[1];
;                             const float a3 = x1[3] * cs1[2] - x2[3] * cs1[3], b3 = x2[3] * cs1[2] + x1[3] * cs1[3];
;                             if (n == 0) { w1.x = cvt_pk_bf16(a0, a1); w1.y = cvt_pk_bf16(a2, a3); w2.x = cvt_pk_bf16(b0, b1); w2.y = cvt_pk_bf16(b2, b3); }
;                             else        { w1.z = cvt_pk_bf16(a0, a1); w1.w = cvt_pk_bf16(a2, a3); w2.z = cvt_pk_bf16(b0, b1); w2.w = cvt_pk_bf16(b2, b3); }
;                         }
;                         bf16_t* rowp = dst + (size_t)row * RW;
;                         *(u32x4*)rowp = w1; *(u32x4*)(rowp + HALF) = w2;
	v_pk_mul_f32 v[234:235], v[126:127], v[170:171] op_sel:[0,0] op_sel_hi:[0,1]
	v_pk_mul_f32 v[236:237], v[126:127], v[172:173] op_sel:[1,0] op_sel_hi:[1,1]
	v_pk_mul_f32 v[238:239], v[128:129], v[174:175] op_sel:[0,0] op_sel_hi:[0,1]
	v_pk_mul_f32 v[240:241], v[128:129], v[176:177] op_sel:[1,0] op_sel_hi:[1,1]
	v_pk_mul_f32 v[242:243], v[122:123], v[178:179] op_sel:[0,0] op_sel_hi:[0,1]
	v_pk_mul_f32 v[244:245], v[122:123], v[180:181] op_sel:[1,0] op_sel_hi:[1,1]
	v_pk_mul_f32 v[246:247], v[124:125], v[182:183] op_sel:[0,0] op_sel_hi:[0,1]
	v_pk_mul_f32 v[248:249], v[124:125], v[184:185] op_sel:[1,0] op_sel_hi:[1,1]
	v_pk_mul_f32 v[170:171], v[118:119], v[170:171] op_sel:[0,0] op_sel_hi:[0,1]
	v_pk_mul_f32 v[172:173], v[118:119], v[172:173] op_sel:[1,0] op_sel_hi:[1,1]
	v_pk_mul_f32 v[174:175], v[120:121], v[174:175] op_sel:[0,0] op_sel_hi:[0,1]
	v_pk_mul_f32 v[176:177], v[120:121], v[176:177] op_sel:[1,0] op_sel_hi:[1,1]
	v_pk_mul_f32 v[178:179], v[110:111], v[178:179] op_sel:[0,0] op_sel_hi:[0,1]
	v_pk_mul_f32 v[180:181], v[110:111], v[180:181] op_sel:[1,0] op_sel_hi:[1,1]
	v_pk_mul_f32 v[182:183], v[112:113], v[182:183] op_sel:[0,0] op_sel_hi:[0,1]
	v_pk_mul_f32 v[184:185], v[112:113], v[184:185] op_sel:[1,0] op_sel_hi:[1,1]
	v_pk_add_f32 v[234:235], v[234:235], v[170:171] op_sel:[0,1] op_sel_hi:[1,0] neg_lo:[0,1]
	v_pk_add_f32 v[236:237], v[236:237], v[172:173] op_sel:[0,1] op_sel_hi:[1,0] neg_lo:[0,1]
	v_pk_add_f32 v[238:239], v[238:239], v[174:175] op_sel:[0,1] op_sel_hi:[1,0] neg_lo:[0,1]
	v_pk_add_f32 v[240:241], v[240:241], v[176:177] op_sel:[0,1] op_sel_hi:[1,0] neg_lo:[0,1]
	v_pk_add_f32 v[242:243], v[242:243], v[178:179] op_sel:[0,1] op_sel_hi:[1,0] neg_lo:[0,1]
	v_pk_add_f32 v[244:245], v[244:245], v[180:181] op_sel:[0,1] op_sel_hi:[1,0] neg_lo:[0,1]
	v_pk_add_f32 v[246:247], v[246:247], v[182:183] op_sel:[0,1] op_sel_hi:[1,0] neg_lo:[0,1]
	v_pk_add_f32 v[248:249], v[248:249], v[184:185] op_sel:[0,1] op_sel_hi:[1,0] neg_lo:[0,1]
	v_cvt_pk_bf16_f32 v170, v234, v236
	v_cvt_pk_bf16_f32 v171, v238, v240
	v_cvt_pk_bf16_f32 v172, v242, v244
	v_cvt_pk_bf16_f32 v173, v246, v248
	v_cvt_pk_bf16_f32 v174, v235, v237
	v_cvt_pk_bf16_f32 v175, v239, v241
	v_cvt_pk_bf16_f32 v176, v243, v245
	v_cvt_pk_bf16_f32 v177, v247, v249
	global_store_dwordx4 v[250:251], v[170:173], off
	global_store_dwordx4 v[250:251], v[174:177], off offset:256
	s_and_b64 s[12:13], vcc, exec
	s_cselect_b32 s98, 0x20000, 0
	s_add_u32 s98, s8, s98
	s_addc_u32 s99, s9, 0
	global_load_dwordx4 v[178:181], v159, s[98:99] offset:32
	global_load_dwordx4 v[182:185], v159, s[98:99] offset:48
	global_load_dwordx4 v[170:173], v159, s[98:99]
	global_load_dwordx4 v[174:177], v159, s[98:99] offset:16
	s_waitcnt vmcnt(14)
	v_pk_mul_f32 v[234:235], v[114:115], v[186:187] op_sel:[0,0] op_sel_hi:[0,1]
	v_pk_mul_f32 v[236:237], v[114:115], v[188:189] op_sel:[1,0] op_sel_hi:[1,1]
	v_pk_mul_f32 v[238:239], v[116:117], v[190:191] op_sel:[0,0] op_sel_hi:[0,1]
	v_pk_mul_f32 v[240:241], v[116:117], v[192:193] op_sel:[1,0] op_sel_hi:[1,1]
	v_pk_mul_f32 v[242:243], v[106:107], v[194:195] op_sel:[0,0] op_sel_hi:[0,1]
	v_pk_mul_f32 v[244:245], v[106:107], v[196:197] op_sel:[1,0] op_sel_hi:[1,1]
	v_pk_mul_f32 v[246:247], v[108:109], v[198:199] op_sel:[0,0] op_sel_hi:[0,1]
	v_pk_mul_f32 v[248:249], v[108:109], v[200:201] op_sel:[1,0] op_sel_hi:[1,1]
	v_pk_mul_f32 v[186:187], v[102:103], v[186:187] op_sel:[0,0] op_sel_hi:[0,1]
	v_pk_mul_f32 v[188:189], v[102:103], v[188:189] op_sel:[1,0] op_sel_hi:[1,1]
	v_pk_mul_f32 v[190:191], v[104:105], v[190:191] op_sel:[0,0] op_sel_hi:[0,1]
	v_pk_mul_f32 v[192:193], v[104:105], v[192:193] op_sel:[1,0] op_sel_hi:[1,1]
	v_pk_mul_f32 v[194:195], v[94:95], v[194:195] op_sel:[0,0] op_sel_hi:[0,1]
	v_pk_mul_f32 v[196:197], v[94:95], v[196:197] op_sel:[1,0] op_sel_hi:[1,1]
	v_pk_mul_f32 v[198:199], v[96:97], v[198:199] op_sel:[0,0] op_sel_hi:[0,1]
	v_pk_mul_f32 v[200:201], v[96:97], v[200:201] op_sel:[1,0] op_sel_hi:[1,1]
	v_pk_add_f32 v[234:235], v[234:235], v[186:187] op_sel:[0,1] op_sel_hi:[1,0] neg_lo:[0,1]
	v_pk_add_f32 v[236:237], v[236:237], v[188:189] op_sel:[0,1] op_sel_hi:[1,0] neg_lo:[0,1]
	v_pk_add_f32 v[238:239], v[238:239], v[190:191] op_sel:[0,1] op_sel_hi:[1,0] neg_lo:[0,1]
	v_pk_add_f32 v[240:241], v[240:241], v[192:193] op_sel:[0,1] op_sel_hi:[1,0] neg_lo:[0,1]
	v_pk_add_f32 v[242:243], v[242:243], v[194:195] op_sel:[0,1] op_sel_hi:[1,0] neg_lo:[0,1]
	v_pk_add_f32 v[244:245], v[244:245], v[196:197] op_sel:[0,1] op_sel_hi:[1,0] neg_lo:[0,1]
	v_pk_add_f32 v[246:247], v[246:247], v[198:199] op_sel:[0,1] op_sel_hi:[1,0] neg_lo:[0,1]
	v_pk_add_f32 v[248:249], v[248:249], v[200:201] op_sel:[0,1] op_sel_hi:[1,0] neg_lo:[0,1]
	v_cvt_pk_bf16_f32 v186, v234, v236
	v_cvt_pk_bf16_f32 v187, v238, v240
	v_cvt_pk_bf16_f32 v188, v242, v244
	v_cvt_pk_bf16_f32 v189, v246, v248
	v_cvt_pk_bf16_f32 v190, v235, v237
	v_cvt_pk_bf16_f32 v191, v239, v241
	v_cvt_pk_bf16_f32 v192, v243, v245
	v_cvt_pk_bf16_f32 v193, v247, v249
	s_mov_b32 s12, 0x8000
	s_mov_b32 s13, 0
	v_lshl_add_u64 v[250:251], v[250:251], 0, s[12:13]
	global_store_dwordx4 v[250:251], v[186:189], off
	global_store_dwordx4 v[250:251], v[190:193], off offset:256
	s_and_b64 s[12:13], vcc, exec
	s_cselect_b32 s98, 0x24000, 0
	s_add_u32 s98, s8, s98
	s_addc_u32 s99, s9, 0
	global_load_dwordx4 v[194:197], v159, s[98:99] offset:32
	global_load_dwordx4 v[198:201], v159, s[98:99] offset:48
	global_load_dwordx4 v[186:189], v159, s[98:99]
	global_load_dwordx4 v[190:193], v159, s[98:99] offset:16
	s_waitcnt vmcnt(16)
; __device__ __forceinline__ unsigned cvt_pk_bf16(float lo, float hi) { unsigned r; asm volatile("v_cvt_pk_bf16_f32 %0, %1, %2" : "=v"(r) : "v"(lo), "v"(hi)); return r; }
;     __device__ __forceinline__ void operator()(const f32x4 (&acc)[2][2][4][2], const Unit& u, int wr, int wc, int fr, int fq) const {
;     ...
;                         const int row = row0 + ai * HALF + m * 16;
;                         const float* rp = rot + ((size_t)ptab_of(row) * 128 + cw) * 2;
;                         u32x4 w1, w2;
; #pragma unroll
;                         for (int n = 0; n < 2; ++n) {
;                             const f32x4 cs0 = *(const f32x4*)(rp + 8 * n), cs1 = *(const f32x4*)(rp + 8 * n + 4);
;                             const f32x4 x1 = acc[ai][0][m][n] * sc, x2 = acc[ai][1][m][n] * sc;
;                             const float a0 = x1[0] * cs0[0] - x2[0] * cs0[1], b0 = x2[0] * cs0[0] + x1[0] * cs0[1];
;                             const float a1 = x1[1] * cs0[2] - x2[1] * cs0[3], b1 = x2[1] * cs0[2] + x1[1] * cs0[3];
;                             const float a2 = x1[2] * cs1[0] - x2[2] * cs1[1], b2 = x2[2] * cs1[0] + x1[2] * cs1[1];
;                             const float a3 = x1[3] * cs1[2] - x2[3] * cs1[3], b3 = x2[3] * cs1[2] + x1[3] * cs1[3];
;                             if (n == 0) { w1.x = cvt_pk_bf16(a0, a1); w1.y = cvt_pk_bf16(a2, a3); w2.x = cvt_pk_bf16(b0, b1); w2.y = cvt_pk_bf16(b2, b3); }
;                             else        { w1.z = cvt_pk_bf16(a0, a1); w1.w = cvt_pk_bf16(a2, a3); w2.z = cvt_pk_bf16(b0, b1); w2.w = cvt_pk_bf16(b2, b3); }
;                         }
;                         bf16_t* rowp = dst + (size_t)row * RW;
;                         *(u32x4*)rowp = w1; *(u32x4*)(rowp + HALF) = w2;
	v_pk_mul_f32 v[234:235], v[98:99], v[202:203] op_sel:[0,0] op_sel_hi:[0,1]
	v_pk_mul_f32 v[236:237], v[98:99], v[204:205] op_sel:[1,0] op_sel_hi:[1,1]
	v_pk_mul_f32 v[238:239], v[100:101], v[206:207] op_sel:[0,0] op_sel_hi:[0,1]
	v_pk_mul_f32 v[240:241], v[100:101], v[208:209] op_sel:[1,0] op_sel_hi:[1,1]
	v_pk_mul_f32 v[242:243], v[90:91], v[210:211] op_sel:[0,0] op_sel_hi:[0,1]
	v_pk_mul_f32 v[244:245], v[90:91], v[212:213] op_sel:[1,0] op_sel_hi:[1,1]
	v_pk_mul_f32 v[246:247], v[92:93], v[214:215] op_sel:[0,0] op_sel_hi:[0,1]
	v_pk_mul_f32 v[248:249], v[92:93], v[216:217] op_sel:[1,0] op_sel_hi:[1,1]
	v_pk_mul_f32 v[202:203], v[86:87], v[202:203] op_sel:[0,0] op_sel_hi:[0,1]
	v_pk_mul_f32 v[204:205], v[86:87], v[204:205] op_sel:[1,0] op_sel_hi:[1,1]
	v_pk_mul_f32 v[206:207], v[88:89], v[206:207] op_sel:[0,0] op_sel_hi:[0,1]
	v_pk_mul_f32 v[208:209], v[88:89], v[208:209] op_sel:[1,0] op_sel_hi:[1,1]
	v_pk_mul_f32 v[210:211], v[78:79], v[210:211] op_sel:[0,0] op_sel_hi:[0,1]
	v_pk_mul_f32 v[212:213], v[78:79], v[212:213] op_sel:[1,0] op_sel_hi:[1,1]
	v_pk_mul_f32 v[214:215], v[80:81], v[214:215] op_sel:[0,0] op_sel_hi:[0,1]
	v_pk_mul_f32 v[216:217], v[80:81], v[216:217] op_sel:[1,0] op_sel_hi:[1,1]
	v_pk_add_f32 v[234:235], v[234:235], v[202:203] op_sel:[0,1] op_sel_hi:[1,0] neg_lo:[0,1]
	v_pk_add_f32 v[236:237], v[236:237], v[204:205] op_sel:[0,1] op_sel_hi:[1,0] neg_lo:[0,1]
	v_pk_add_f32 v[238:239], v[238:239], v[206:207] op_sel:[0,1] op_sel_hi:[1,0] neg_lo:[0,1]
	v_pk_add_f32 v[240:241], v[240:241], v[208:209] op_sel:[0,1] op_sel_hi:[1,0] neg_lo:[0,1]
	v_pk_add_f32 v[242:243], v[242:243], v[210:211] op_sel:[0,1] op_sel_hi:[1,0] neg_lo:[0,1]
	v_pk_add_f32 v[244:245], v[244:245], v[212:213] op_sel:[0,1] op_sel_hi:[1,0] neg_lo:[0,1]
	v_pk_add_f32 v[246:247], v[246:247], v[214:215] op_sel:[0,1] op_sel_hi:[1,0] neg_lo:[0,1]
	v_pk_add_f32 v[248:249], v[248:249], v[216:217] op_sel:[0,1] op_sel_hi:[1,0] neg_lo:[0,1]
	v_cvt_pk_bf16_f32 v202, v234, v236
	v_cvt_pk_bf16_f32 v203, v238, v240
	v_cvt_pk_bf16_f32 v204, v242, v244
	v_cvt_pk_bf16_f32 v205, v246, v248
	v_cvt_pk_bf16_f32 v206, v235, v237
	v_cvt_pk_bf16_f32 v207, v239, v241
	v_cvt_pk_bf16_f32 v208, v243, v245
	v_cvt_pk_bf16_f32 v209, v247, v249
	s_mov_b32 s12, 0x8000
	s_mov_b32 s13, 0
	v_lshl_add_u64 v[250:251], v[250:251], 0, s[12:13]
	global_store_dwordx4 v[250:251], v[202:205], off
	global_store_dwordx4 v[250:251], v[206:209], off offset:256
	s_and_b64 s[12:13], vcc, exec
	s_cselect_b32 s98, 0x28000, 0
	s_add_u32 s98, s8, s98
	s_addc_u32 s99, s9, 0
	global_load_dwordx4 v[210:213], v159, s[98:99] offset:32
	global_load_dwordx4 v[214:217], v159, s[98:99] offset:48
	global_load_dwordx4 v[202:205], v159, s[98:99]
	global_load_dwordx4 v[206:209], v159, s[98:99] offset:16
	s_waitcnt vmcnt(18)
	v_pk_mul_f32 v[234:235], v[82:83], v[218:219] op_sel:[0,0] op_sel_hi:[0,1]
	v_pk_mul_f32 v[236:237], v[82:83], v[220:221] op_sel:[1,0] op_sel_hi:[1,1]
	v_pk_mul_f32 v[238:239], v[84:85], v[222:223] op_sel:[0,0] op_sel_hi:[0,1]
	v_pk_mul_f32 v[240:241], v[84:85], v[224:225] op_sel:[1,0] op_sel_hi:[1,1]
	v_pk_mul_f32 v[242:243], v[74:75], v[226:227] op_sel:[0,0] op_sel_hi:[0,1]
	v_pk_mul_f32 v[244:245], v[74:75], v[228:229] op_sel:[1,0] op_sel_hi:[1,1]
	v_pk_mul_f32 v[246:247], v[76:77], v[230:231] op_sel:[0,0] op_sel_hi:[0,1]
	v_pk_mul_f32 v[248:249], v[76:77], v[232:233] op_sel:[1,0] op_sel_hi:[1,1]
	v_pk_mul_f32 v[218:219], v[70:71], v[218:219] op_sel:[0,0] op_sel_hi:[0,1]
	v_pk_mul_f32 v[220:221], v[70:71], v[220:221] op_sel:[1,0] op_sel_hi:[1,1]
	v_pk_mul_f32 v[222:223], v[72:73], v[222:223] op_sel:[0,0] op_sel_hi:[0,1]
	v_pk_mul_f32 v[224:225], v[72:73], v[224:225] op_sel:[1,0] op_sel_hi:[1,1]
	v_pk_mul_f32 v[226:227], v[66:67], v[226:227] op_sel:[0,0] op_sel_hi:[0,1]
	v_pk_mul_f32 v[228:229], v[66:67], v[228:229] op_sel:[1,0] op_sel_hi:[1,1]
	v_pk_mul_f32 v[230:231], v[68:69], v[230:231] op_sel:[0,0] op_sel_hi:[0,1]
	v_pk_mul_f32 v[232:233], v[68:69], v[232:233] op_sel:[1,0] op_sel_hi:[1,1]
	v_pk_add_f32 v[234:235], v[234:235], v[218:219] op_sel:[0,1] op_sel_hi:[1,0] neg_lo:[0,1]
	v_pk_add_f32 v[236:237], v[236:237], v[220:221] op_sel:[0,1] op_sel_hi:[1,0] neg_lo:[0,1]
	v_pk_add_f32 v[238:239], v[238:239], v[222:223] op_sel:[0,1] op_sel_hi:[1,0] neg_lo:[0,1]
	v_pk_add_f32 v[240:241], v[240:241], v[224:225] op_sel:[0,1] op_sel_hi:[1,0] neg_lo:[0,1]
	v_pk_add_f32 v[242:243], v[242:243], v[226:227] op_sel:[0,1] op_sel_hi:[1,0] neg_lo:[0,1]
	v_pk_add_f32 v[244:245], v[244:245], v[228:229] op_sel:[0,1] op_sel_hi:[1,0] neg_lo:[0,1]
	v_pk_add_f32 v[246:247], v[246:247], v[230:231] op_sel:[0,1] op_sel_hi:[1,0] neg_lo:[0,1]
	v_pk_add_f32 v[248:249], v[248:249], v[232:233] op_sel:[0,1] op_sel_hi:[1,0] neg_lo:[0,1]
	v_cvt_pk_bf16_f32 v218, v234, v236
	v_cvt_pk_bf16_f32 v219, v238, v240
	v_cvt_pk_bf16_f32 v220, v242, v244
	v_cvt_pk_bf16_f32 v221, v246, v248
	v_cvt_pk_bf16_f32 v222, v235, v237
	v_cvt_pk_bf16_f32 v223, v239, v241
	v_cvt_pk_bf16_f32 v224, v243, v245
	v_cvt_pk_bf16_f32 v225, v247, v249
	s_mov_b32 s12, 0x8000
	s_mov_b32 s13, 0
	v_lshl_add_u64 v[250:251], v[250:251], 0, s[12:13]
	global_store_dwordx4 v[250:251], v[218:221], off
	global_store_dwordx4 v[250:251], v[222:225], off offset:256
	s_and_b64 s[12:13], vcc, exec
	s_cselect_b32 s98, 0x2c000, 0
	s_add_u32 s98, s8, s98
	s_addc_u32 s99, s9, 0
	global_load_dwordx4 v[226:229], v159, s[98:99] offset:32
	global_load_dwordx4 v[230:233], v159, s[98:99] offset:48
	global_load_dwordx4 v[218:221], v159, s[98:99]
	global_load_dwordx4 v[222:225], v159, s[98:99] offset:16
	s_waitcnt vmcnt(18)
; __device__ __forceinline__ unsigned cvt_pk_bf16(float lo, float hi) { unsigned r; asm volatile("v_cvt_pk_bf16_f32 %0, %1, %2" : "=v"(r) : "v"(lo), "v"(hi)); return r; }
;     __device__ __forceinline__ void operator()(const f32x4 (&acc)[2][2][4][2], const Unit& u, int wr, int wc, int fr, int fq) const {
;     ...
;                         const int row = row0 + ai * HALF + m * 16;
;                         const float* rp = rot + ((size_t)ptab_of(row) * 128 + cw) * 2;
;                         u32x4 w1, w2;
; #pragma unroll
;                         for (int n = 0; n < 2; ++n) {
;                             const f32x4 cs0 = *(const f32x4*)(rp + 8 * n), cs1 = *(const f32x4*)(rp + 8 * n + 4);
;                             const f32x4 x1 = acc[ai][0][m][n] * sc, x2 = acc[ai][1][m][n] * sc;
;                             const float a0 = x1[0] * cs0[0] - x2[0] * cs0[1], b0 = x2[0] * cs0[0] + x1[0] * cs0[1];
;                             const float a1 = x1[1] * cs0[2] - x2[1] * cs0[3], b1 = x2[1] * cs0[2] + x1[1] * cs0[3];
;                             const float a2 = x1[2] * cs1[0] - x2[2] * cs1[1], b2 = x2[2] * cs1[0] + x1[2] * cs1[1];
;                             const float a3 = x1[3] * cs1[2] - x2[3] * cs1[3], b3 = x2[3] * cs1[2] + x1[3] * cs1[3];
;                             if (n == 0) { w1.x = cvt_pk_bf16(a0, a1); w1.y = cvt_pk_bf16(a2, a3); w2.x = cvt_pk_bf16(b0, b1); w2.y = cvt_pk_bf16(b2, b3); }
;                             else        { w1.z = cvt_pk_bf16(a0, a1); w1.w = cvt_pk_bf16(a2, a3); w2.z = cvt_pk_bf16(b0, b1); w2.w = cvt_pk_bf16(b2, b3); }
;                         }
;                         bf16_t* rowp = dst + (size_t)row * RW;
;                         *(u32x4*)rowp = w1; *(u32x4*)(rowp + HALF) = w2;
	v_pk_mul_f32 v[234:235], v[62:63], v[170:171] op_sel:[0,0] op_sel_hi:[0,1]
	v_pk_mul_f32 v[236:237], v[62:63], v[172:173] op_sel:[1,0] op_sel_hi:[1,1]
	v_pk_mul_f32 v[238:239], v[64:65], v[174:175] op_sel:[0,0] op_sel_hi:[0,1]
	v_pk_mul_f32 v[240:241], v[64:65], v[176:177] op_sel:[1,0] op_sel_hi:[1,1]
	v_pk_mul_f32 v[242:243], v[58:59], v[178:179] op_sel:[0,0] op_sel_hi:[0,1]
	v_pk_mul_f32 v[244:245], v[58:59], v[180:181] op_sel:[1,0] op_sel_hi:[1,1]
	v_pk_mul_f32 v[246:247], v[60:61], v[182:183] op_sel:[0,0] op_sel_hi:[0,1]
	v_pk_mul_f32 v[248:249], v[60:61], v[184:185] op_sel:[1,0] op_sel_hi:[1,1]
	v_pk_mul_f32 v[170:171], v[50:51], v[170:171] op_sel:[0,0] op_sel_hi:[0,1]
	v_pk_mul_f32 v[172:173], v[50:51], v[172:173] op_sel:[1,0] op_sel_hi:[1,1]
	v_pk_mul_f32 v[174:175], v[52:53], v[174:175] op_sel:[0,0] op_sel_hi:[0,1]
	v_pk_mul_f32 v[176:177], v[52:53], v[176:177] op_sel:[1,0] op_sel_hi:[1,1]
	v_pk_mul_f32 v[178:179], v[42:43], v[178:179] op_sel:[0,0] op_sel_hi:[0,1]
	v_pk_mul_f32 v[180:181], v[42:43], v[180:181] op_sel:[1,0] op_sel_hi:[1,1]
	v_pk_mul_f32 v[182:183], v[44:45], v[182:183] op_sel:[0,0] op_sel_hi:[0,1]
	v_pk_mul_f32 v[184:185], v[44:45], v[184:185] op_sel:[1,0] op_sel_hi:[1,1]
	v_pk_add_f32 v[234:235], v[234:235], v[170:171] op_sel:[0,1] op_sel_hi:[1,0] neg_lo:[0,1]
	v_pk_add_f32 v[236:237], v[236:237], v[172:173] op_sel:[0,1] op_sel_hi:[1,0] neg_lo:[0,1]
	v_pk_add_f32 v[238:239], v[238:239], v[174:175] op_sel:[0,1] op_sel_hi:[1,0] neg_lo:[0,1]
	v_pk_add_f32 v[240:241], v[240:241], v[176:177] op_sel:[0,1] op_sel_hi:[1,0] neg_lo:[0,1]
	v_pk_add_f32 v[242:243], v[242:243], v[178:179] op_sel:[0,1] op_sel_hi:[1,0] neg_lo:[0,1]
	v_pk_add_f32 v[244:245], v[244:245], v[180:181] op_sel:[0,1] op_sel_hi:[1,0] neg_lo:[0,1]
	v_pk_add_f32 v[246:247], v[246:247], v[182:183] op_sel:[0,1] op_sel_hi:[1,0] neg_lo:[0,1]
	v_pk_add_f32 v[248:249], v[248:249], v[184:185] op_sel:[0,1] op_sel_hi:[1,0] neg_lo:[0,1]
	v_cvt_pk_bf16_f32 v170, v234, v236
	v_cvt_pk_bf16_f32 v171, v238, v240
	v_cvt_pk_bf16_f32 v172, v242, v244
	v_cvt_pk_bf16_f32 v173, v246, v248
	v_cvt_pk_bf16_f32 v174, v235, v237
	v_cvt_pk_bf16_f32 v175, v239, v241
	v_cvt_pk_bf16_f32 v176, v243, v245
	v_cvt_pk_bf16_f32 v177, v247, v249
	s_mov_b32 s12, 0x28000
	s_mov_b32 s13, 0
	v_lshl_add_u64 v[250:251], v[250:251], 0, s[12:13]
	global_store_dwordx4 v[250:251], v[170:173], off
	global_store_dwordx4 v[250:251], v[174:177], off offset:256
	s_waitcnt vmcnt(14)
	v_pk_mul_f32 v[234:235], v[54:55], v[186:187] op_sel:[0,0] op_sel_hi:[0,1]
	v_pk_mul_f32 v[236:237], v[54:55], v[188:189] op_sel:[1,0] op_sel_hi:[1,1]
	v_pk_mul_f32 v[238:239], v[56:57], v[190:191] op_sel:[0,0] op_sel_hi:[0,1]
	v_pk_mul_f32 v[240:241], v[56:57], v[192:193] op_sel:[1,0] op_sel_hi:[1,1]
	v_pk_mul_f32 v[242:243], v[46:47], v[194:195] op_sel:[0,0] op_sel_hi:[0,1]
	v_pk_mul_f32 v[244:245], v[46:47], v[196:197] op_sel:[1,0] op_sel_hi:[1,1]
	v_pk_mul_f32 v[246:247], v[48:49], v[198:199] op_sel:[0,0] op_sel_hi:[0,1]
	v_pk_mul_f32 v[248:249], v[48:49], v[200:201] op_sel:[1,0] op_sel_hi:[1,1]
	v_pk_mul_f32 v[186:187], v[34:35], v[186:187] op_sel:[0,0] op_sel_hi:[0,1]
	v_pk_mul_f32 v[188:189], v[34:35], v[188:189] op_sel:[1,0] op_sel_hi:[1,1]
	v_pk_mul_f32 v[190:191], v[36:37], v[190:191] op_sel:[0,0] op_sel_hi:[0,1]
	v_pk_mul_f32 v[192:193], v[36:37], v[192:193] op_sel:[1,0] op_sel_hi:[1,1]
	v_pk_mul_f32 v[194:195], v[26:27], v[194:195] op_sel:[0,0] op_sel_hi:[0,1]
	v_pk_mul_f32 v[196:197], v[26:27], v[196:197] op_sel:[1,0] op_sel_hi:[1,1]
	v_pk_mul_f32 v[198:199], v[28:29], v[198:199] op_sel:[0,0] op_sel_hi:[0,1]
	v_pk_mul_f32 v[200:201], v[28:29], v[200:201] op_sel:[1,0] op_sel_hi:[1,1]
	v_pk_add_f32 v[234:235], v[234:235], v[186:187] op_sel:[0,1] op_sel_hi:[1,0] neg_lo:[0,1]
	v_pk_add_f32 v[236:237], v[236:237], v[188:189] op_sel:[0,1] op_sel_hi:[1,0] neg_lo:[0,1]
	v_pk_add_f32 v[238:239], v[238:239], v[190:191] op_sel:[0,1] op_sel_hi:[1,0] neg_lo:[0,1]
	v_pk_add_f32 v[240:241], v[240:241], v[192:193] op_sel:[0,1] op_sel_hi:[1,0] neg_lo:[0,1]
	v_pk_add_f32 v[242:243], v[242:243], v[194:195] op_sel:[0,1] op_sel_hi:[1,0] neg_lo:[0,1]
	v_pk_add_f32 v[244:245], v[244:245], v[196:197] op_sel:[0,1] op_sel_hi:[1,0] neg_lo:[0,1]
	v_pk_add_f32 v[246:247], v[246:247], v[198:199] op_sel:[0,1] op_sel_hi:[1,0] neg_lo:[0,1]
	v_pk_add_f32 v[248:249], v[248:249], v[200:201] op_sel:[0,1] op_sel_hi:[1,0] neg_lo:[0,1]
	v_cvt_pk_bf16_f32 v186, v234, v236
	v_cvt_pk_bf16_f32 v187, v238, v240
	v_cvt_pk_bf16_f32 v188, v242, v244
	v_cvt_pk_bf16_f32 v189, v246, v248
	v_cvt_pk_bf16_f32 v190, v235, v237
	v_cvt_pk_bf16_f32 v191, v239, v241
	v_cvt_pk_bf16_f32 v192, v243, v245
	v_cvt_pk_bf16_f32 v193, v247, v249
	s_mov_b32 s12, 0x8000
	s_mov_b32 s13, 0
	v_lshl_add_u64 v[250:251], v[250:251], 0, s[12:13]
	global_store_dwordx4 v[250:251], v[186:189], off
	global_store_dwordx4 v[250:251], v[190:193], off offset:256
	s_waitcnt vmcnt(10)
; __device__ __forceinline__ unsigned cvt_pk_bf16(float lo, float hi) { unsigned r; asm volatile("v_cvt_pk_bf16_f32 %0, %1, %2" : "=v"(r) : "v"(lo), "v"(hi)); return r; }
;     __device__ __forceinline__ void operator()(const f32x4 (&acc)[2][2][4][2], const Unit& u, int wr, int wc, int fr, int fq) const {
;     ...
;                         const int row = row0 + ai * HALF + m * 16;
;                         const float* rp = rot + ((size_t)ptab_of(row) * 128 + cw) * 2;
;                         u32x4 w1, w2;
; #pragma unroll
;                         for (int n = 0; n < 2; ++n) {
;                             const f32x4 cs0 = *(const f32x4*)(rp + 8 * n), cs1 = *(const f32x4*)(rp + 8 * n + 4);
;                             const f32x4 x1 = acc[ai][0][m][n] * sc, x2 = acc[ai][1][m][n] * sc;
;                             const float a0 = x1[0] * cs0[0] - x2[0] * cs0[1], b0 = x2[0] * cs0[0] + x1[0] * cs0[1];
;                             const float a1 = x1[1] * cs0[2] - x2[1] * cs0[3], b1 = x2[1] * cs0[2] + x1[1] * cs0[3];
;                             const float a2 = x1[2] * cs1[0] - x2[2] * cs1[1], b2 = x2[2] * cs1[0] + x1[2] * cs1[1];
;                             const float a3 = x1[3] * cs1[2] - x2[3] * cs1[3], b3 = x2[3] * cs1[2] + x1[3] * cs1[3];
;                             if (n == 0) { w1.x = cvt_pk_bf16(a0, a1); w1.y = cvt_pk_bf16(a2, a3); w2.x = cvt_pk_bf16(b0, b1); w2.y = cvt_pk_bf16(b2, b3); }
;                             else        { w1.z = cvt_pk_bf16(a0, a1); w1.w = cvt_pk_bf16(a2, a3); w2.z = cvt_pk_bf16(b0, b1); w2.w = cvt_pk_bf16(b2, b3); }
;                         }
;                         bf16_t* rowp = dst + (size_t)row * RW;
;                         *(u32x4*)rowp = w1; *(u32x4*)(rowp + HALF) = w2;
	v_pk_mul_f32 v[234:235], v[38:39], v[202:203] op_sel:[0,0] op_sel_hi:[0,1]
	v_pk_mul_f32 v[236:237], v[38:39], v[204:205] op_sel:[1,0] op_sel_hi:[1,1]
	v_pk_mul_f32 v[238:239], v[40:41], v[206:207] op_sel:[0,0] op_sel_hi:[0,1]
	v_pk_mul_f32 v[240:241], v[40:41], v[208:209] op_sel:[1,0] op_sel_hi:[1,1]
	v_pk_mul_f32 v[242:243], v[30:31], v[210:211] op_sel:[0,0] op_sel_hi:[0,1]
	v_pk_mul_f32 v[244:245], v[30:31], v[212:213] op_sel:[1,0] op_sel_hi:[1,1]
	v_pk_mul_f32 v[246:247], v[32:33], v[214:215] op_sel:[0,0] op_sel_hi:[0,1]
	v_pk_mul_f32 v[248:249], v[32:33], v[216:217] op_sel:[1,0] op_sel_hi:[1,1]
	v_pk_mul_f32 v[202:203], v[18:19], v[202:203] op_sel:[0,0] op_sel_hi:[0,1]
	v_pk_mul_f32 v[204:205], v[18:19], v[204:205] op_sel:[1,0] op_sel_hi:[1,1]
	v_pk_mul_f32 v[206:207], v[20:21], v[206:207] op_sel:[0,0] op_sel_hi:[0,1]
	v_pk_mul_f32 v[208:209], v[20:21], v[208:209] op_sel:[1,0] op_sel_hi:[1,1]
	v_pk_mul_f32 v[210:211], v[10:11], v[210:211] op_sel:[0,0] op_sel_hi:[0,1]
	v_pk_mul_f32 v[212:213], v[10:11], v[212:213] op_sel:[1,0] op_sel_hi:[1,1]
	v_pk_mul_f32 v[214:215], v[12:13], v[214:215] op_sel:[0,0] op_sel_hi:[0,1]
	v_pk_mul_f32 v[216:217], v[12:13], v[216:217] op_sel:[1,0] op_sel_hi:[1,1]
	v_pk_add_f32 v[234:235], v[234:235], v[202:203] op_sel:[0,1] op_sel_hi:[1,0] neg_lo:[0,1]
	v_pk_add_f32 v[236:237], v[236:237], v[204:205] op_sel:[0,1] op_sel_hi:[1,0] neg_lo:[0,1]
	v_pk_add_f32 v[238:239], v[238:239], v[206:207] op_sel:[0,1] op_sel_hi:[1,0] neg_lo:[0,1]
	v_pk_add_f32 v[240:241], v[240:241], v[208:209] op_sel:[0,1] op_sel_hi:[1,0] neg_lo:[0,1]
	v_pk_add_f32 v[242:243], v[242:243], v[210:211] op_sel:[0,1] op_sel_hi:[1,0] neg_lo:[0,1]
	v_pk_add_f32 v[244:245], v[244:245], v[212:213] op_sel:[0,1] op_sel_hi:[1,0] neg_lo:[0,1]
	v_pk_add_f32 v[246:247], v[246:247], v[214:215] op_sel:[0,1] op_sel_hi:[1,0] neg_lo:[0,1]
	v_pk_add_f32 v[248:249], v[248:249], v[216:217] op_sel:[0,1] op_sel_hi:[1,0] neg_lo:[0,1]
	v_cvt_pk_bf16_f32 v202, v234, v236
	v_cvt_pk_bf16_f32 v203, v238, v240
	v_cvt_pk_bf16_f32 v204, v242, v244
	v_cvt_pk_bf16_f32 v205, v246, v248
	v_cvt_pk_bf16_f32 v206, v235, v237
	v_cvt_pk_bf16_f32 v207, v239, v241
	v_cvt_pk_bf16_f32 v208, v243, v245
	v_cvt_pk_bf16_f32 v209, v247, v249
	s_mov_b32 s12, 0x8000
	s_mov_b32 s13, 0
	v_lshl_add_u64 v[250:251], v[250:251], 0, s[12:13]
	global_store_dwordx4 v[250:251], v[202:205], off
	global_store_dwordx4 v[250:251], v[206:209], off offset:256
	s_waitcnt vmcnt(6)
	v_pk_mul_f32 v[234:235], v[22:23], v[218:219] op_sel:[0,0] op_sel_hi:[0,1]
	v_pk_mul_f32 v[236:237], v[22:23], v[220:221] op_sel:[1,0] op_sel_hi:[1,1]
	v_pk_mul_f32 v[238:239], v[24:25], v[222:223] op_sel:[0,0] op_sel_hi:[0,1]
	v_pk_mul_f32 v[240:241], v[24:25], v[224:225] op_sel:[1,0] op_sel_hi:[1,1]
	v_pk_mul_f32 v[242:243], v[14:15], v[226:227] op_sel:[0,0] op_sel_hi:[0,1]
	v_pk_mul_f32 v[244:245], v[14:15], v[228:229] op_sel:[1,0] op_sel_hi:[1,1]
	v_pk_mul_f32 v[246:247], v[16:17], v[230:231] op_sel:[0,0] op_sel_hi:[0,1]
	v_pk_mul_f32 v[248:249], v[16:17], v[232:233] op_sel:[1,0] op_sel_hi:[1,1]
	v_pk_mul_f32 v[218:219], v[6:7], v[218:219] op_sel:[0,0] op_sel_hi:[0,1]
	v_pk_mul_f32 v[220:221], v[6:7], v[220:221] op_sel:[1,0] op_sel_hi:[1,1]
	v_pk_mul_f32 v[222:223], v[8:9], v[222:223] op_sel:[0,0] op_sel_hi:[0,1]
	v_pk_mul_f32 v[224:225], v[8:9], v[224:225] op_sel:[1,0] op_sel_hi:[1,1]
	v_pk_mul_f32 v[226:227], v[2:3], v[226:227] op_sel:[0,0] op_sel_hi:[0,1]
	v_pk_mul_f32 v[228:229], v[2:3], v[228:229] op_sel:[1,0] op_sel_hi:[1,1]
	v_pk_mul_f32 v[230:231], v[4:5], v[230:231] op_sel:[0,0] op_sel_hi:[0,1]
	v_pk_mul_f32 v[232:233], v[4:5], v[232:233] op_sel:[1,0] op_sel_hi:[1,1]
	v_pk_add_f32 v[234:235], v[234:235], v[218:219] op_sel:[0,1] op_sel_hi:[1,0] neg_lo:[0,1]
	v_pk_add_f32 v[236:237], v[236:237], v[220:221] op_sel:[0,1] op_sel_hi:[1,0] neg_lo:[0,1]
	v_pk_add_f32 v[238:239], v[238:239], v[222:223] op_sel:[0,1] op_sel_hi:[1,0] neg_lo:[0,1]
	v_pk_add_f32 v[240:241], v[240:241], v[224:225] op_sel:[0,1] op_sel_hi:[1,0] neg_lo:[0,1]
	v_pk_add_f32 v[242:243], v[242:243], v[226:227] op_sel:[0,1] op_sel_hi:[1,0] neg_lo:[0,1]
	v_pk_add_f32 v[244:245], v[244:245], v[228:229] op_sel:[0,1] op_sel_hi:[1,0] neg_lo:[0,1]
	v_pk_add_f32 v[246:247], v[246:247], v[230:231] op_sel:[0,1] op_sel_hi:[1,0] neg_lo:[0,1]
	v_pk_add_f32 v[248:249], v[248:249], v[232:233] op_sel:[0,1] op_sel_hi:[1,0] neg_lo:[0,1]
	v_cvt_pk_bf16_f32 v218, v234, v236
	v_cvt_pk_bf16_f32 v219, v238, v240
	v_cvt_pk_bf16_f32 v220, v242, v244
	v_cvt_pk_bf16_f32 v221, v246, v248
	v_cvt_pk_bf16_f32 v130, v235, v237
	v_cvt_pk_bf16_f32 v131, v239, v241
	v_cvt_pk_bf16_f32 v132, v243, v245
	v_cvt_pk_bf16_f32 v133, v247, v249
	s_mov_b32 s12, 0x8000
	s_mov_b32 s13, 0
	v_lshl_add_u64 v[250:251], v[250:251], 0, s[12:13]
	global_store_dwordx4 v[250:251], v[218:221], off
	v_mov_b32_e32 v162, v250
	v_mov_b32_e32 v163, v251

; __device__ __forceinline__ void retC_unit(Frame& F, int unit) {
;     ...
;     f32x4 acc[16];
; #pragma unroll
;     for (int j = 0; j < 16; ++j) acc[j] = (f32x4){0.f, 0.f, 0.f, 0.f};
;     const int n = 16 * w + fr; const size_t row = (size_t)(m0 + n);
;     const bf16* oip = WSP(bf16, WS_OI) + row * RW + h * HD + 16 * fq;
;     const bf16* gp = Gg + (size_t)n * RW + 16 * fq;
;     v2u oiv[16], gvv[16];
;     if (c == 0) {
;         RETC_LOAD_OG();
;     }
.LBB0_1111:
	global_load_dwordx4 v[58:61], v[170:171], off offset:16 nt
	global_load_dwordx4 v[62:65], v[170:171], off nt
	global_load_dwordx4 v[26:29], v[168:169], off offset:16 nt
	global_load_dwordx4 v[30:33], v[168:169], off nt
	global_load_dwordx4 v[50:53], v[170:171], off offset:144 nt
	global_load_dwordx4 v[54:57], v[170:171], off offset:128 nt
	global_load_dwordx4 v[18:21], v[168:169], off offset:144 nt
	global_load_dwordx4 v[22:25], v[168:169], off offset:128 nt
	global_load_dwordx4 v[46:49], v[170:171], off offset:256 nt
	global_load_dwordx4 v[42:45], v[170:171], off offset:272 nt
	global_load_dwordx4 v[10:13], v[168:169], off offset:272 nt
	global_load_dwordx4 v[14:17], v[168:169], off offset:256 nt
	global_load_dwordx4 v[38:41], v[170:171], off offset:384 nt
	global_load_dwordx4 v[34:37], v[170:171], off offset:400 nt
	global_load_dwordx4 v[2:5], v[168:169], off offset:400 nt
	global_load_dwordx4 v[6:9], v[168:169], off offset:384 nt
	v_mov_b32_e32 v114, 0
	v_mov_b32_e32 v115, v114
	v_mov_b32_e32 v116, v114
	v_mov_b32_e32 v117, v114
	v_mov_b32_e32 v126, v114
	v_mov_b32_e32 v127, v114
	v_mov_b32_e32 v128, v114
	v_mov_b32_e32 v129, v114
	v_mov_b32_e32 v122, v114
	v_mov_b32_e32 v123, v114
	v_mov_b32_e32 v124, v114
	v_mov_b32_e32 v125, v114
	v_mov_b32_e32 v118, v114
	v_mov_b32_e32 v119, v114
	v_mov_b32_e32 v120, v114
	v_mov_b32_e32 v121, v114
	v_mov_b32_e32 v110, v114
	v_mov_b32_e32 v111, v114
	v_mov_b32_e32 v112, v114
	v_mov_b32_e32 v113, v114
	v_mov_b32_e32 v106, v114
	v_mov_b32_e32 v107, v114
	v_mov_b32_e32 v108, v114
	v_mov_b32_e32 v109, v114
	v_mov_b32_e32 v102, v114
	v_mov_b32_e32 v103, v114
	v_mov_b32_e32 v104, v114
	v_mov_b32_e32 v105, v114
	v_mov_b32_e32 v98, v114
	v_mov_b32_e32 v99, v114
	v_mov_b32_e32 v100, v114
	v_mov_b32_e32 v101, v114
	v_mov_b32_e32 v94, v114
	v_mov_b32_e32 v95, v114
	v_mov_b32_e32 v96, v114
	v_mov_b32_e32 v97, v114
	v_mov_b32_e32 v90, v114
	v_mov_b32_e32 v91, v114
	v_mov_b32_e32 v92, v114
	v_mov_b32_e32 v93, v114
	v_mov_b32_e32 v86, v114
	v_mov_b32_e32 v87, v114
	v_mov_b32_e32 v88, v114
	v_mov_b32_e32 v89, v114
	v_mov_b32_e32 v82, v114
	v_mov_b32_e32 v83, v114
	v_mov_b32_e32 v84, v114
	v_mov_b32_e32 v85, v114
	v_mov_b32_e32 v74, v114
	v_mov_b32_e32 v75, v114
	v_mov_b32_e32 v76, v114
	v_mov_b32_e32 v77, v114
	v_mov_b32_e32 v70, v114
	v_mov_b32_e32 v71, v114
	v_mov_b32_e32 v72, v114
	v_mov_b32_e32 v73, v114
	v_mov_b32_e32 v66, v114
	v_mov_b32_e32 v67, v114
	v_mov_b32_e32 v68, v114
	v_mov_b32_e32 v69, v114
	v_mov_b32_e32 v78, v114
	v_mov_b32_e32 v79, v114
	v_mov_b32_e32 v80, v114
	v_mov_b32_e32 v81, v114

; #define LAS __attribute__((address_space(3)))
; __device__ __forceinline__ void retC_unit(Frame& F, int unit) {
;     ...
;     if (c > 0) {
;         const bf16* STc = WSP(bf16, WS_ST) + (size_t)(bh * NCH + c) * HD * HD;
;         {
;             v4u st[16];
; #pragma unroll
;             for (int it = 0; it < 16; ++it) st[it] = *(const v4u*)(STc + (size_t)(it * 512 + tid) * 8);
; #pragma unroll
;             for (int it = 0; it < 16; ++it) { const int idx = it * 512 + tid, row = idx >> 5, ch = idx & 31;
;                 *(LAS v4u*)(F.lds + row * 512 + ((ch ^ ((((row >> 4) & 3) << 2) | (row & 3))) * 16)) = st[it]; }
;         }
;         bf16x8 qf[8];
; #pragma unroll
;         for (int s = 0; s < 8; ++s) qf[s] = *(const bf16x8*)(Qg + (size_t)(16 * w + fr) * RW + 32 * s + 8 * fq);
;         RETC_LOAD_OG();
;         __syncthreads();
.LBB0_1118:
	s_and_b32 s26, s22, 15
	s_and_b32 s0, s17, 0xfffff800
	s_lshl_b32 s1, s26, 7
	v_and_b32_e32 v86, 15, v88
	s_or_b32 s24, s0, s1
	v_or_b32_e32 v162, s16, v86
	s_ashr_i32 s25, s24, 31
	v_add_u32_e32 v2, s24, v162
	s_lshl_b64 s[0:1], s[24:25], 11
	v_ashrrev_i32_e32 v3, 31, v2
	s_add_u32 s0, s14, s0
	v_lshlrev_b64 v[164:165], 11, v[2:3]
	v_and_b32_e32 v166, -16, v88
	s_addc_u32 s1, s15, s1
	s_lshl_b32 s4, s23, 9
	v_lshl_add_u64 v[2:3], s[2:3], 0, v[164:165]
	v_ashrrev_i32_e32 v167, 31, v166
	s_add_u32 s0, s0, s4
	v_lshl_add_u64 v[2:3], v[2:3], 0, s[4:5]
	v_lshlrev_b64 v[4:5], 1, v[166:167]
	s_addc_u32 s1, s1, 0
	v_lshl_add_u64 v[170:171], v[2:3], 0, v[4:5]
	v_lshlrev_b64 v[2:3], 11, v[162:163]
	v_lshl_add_u64 v[2:3], s[0:1], 0, v[2:3]
	v_lshl_add_u64 v[2:3], v[2:3], 0, v[4:5]
	s_cmp_lg_u32 s26, 0
	v_lshl_add_u64 v[168:169], v[2:3], 0, s[10:11]
	s_cbranch_scc0 .LBB0_1120
	v_lshl_add_u64 v[2:3], s[6:7], 0, v[160:161]
	v_lshl_add_u64 v[4:5], s[6:7], 0, v[158:159]
	global_load_dwordx4 v[90:93], v[2:3], off nt
	global_load_dwordx4 v[94:97], v[4:5], off nt
	v_lshl_add_u64 v[2:3], s[6:7], 0, v[156:157]
	v_lshl_add_u64 v[4:5], s[6:7], 0, v[154:155]
	global_load_dwordx4 v[98:101], v[2:3], off nt
	global_load_dwordx4 v[102:105], v[4:5], off nt
	v_lshl_add_u64 v[2:3], s[6:7], 0, v[152:153]
	v_lshl_add_u64 v[4:5], s[6:7], 0, v[150:151]
	global_load_dwordx4 v[106:109], v[2:3], off nt
	global_load_dwordx4 v[110:113], v[4:5], off nt
	v_lshl_add_u64 v[2:3], s[6:7], 0, v[148:149]
	v_lshl_add_u64 v[4:5], s[6:7], 0, v[146:147]
	global_load_dwordx4 v[114:117], v[2:3], off nt
	global_load_dwordx4 v[118:121], v[4:5], off nt
	v_lshl_add_u64 v[2:3], s[6:7], 0, v[144:145]
	v_lshl_add_u64 v[4:5], s[6:7], 0, v[142:143]
	global_load_dwordx4 v[122:125], v[2:3], off nt
	global_load_dwordx4 v[126:129], v[4:5], off nt
	v_lshl_add_u64 v[2:3], s[6:7], 0, v[140:141]
	v_lshl_add_u64 v[4:5], s[6:7], 0, v[138:139]
	global_load_dwordx4 v[196:199], v[2:3], off nt
	global_load_dwordx4 v[200:203], v[4:5], off nt
	v_lshl_add_u64 v[2:3], s[6:7], 0, v[136:137]
	v_lshl_add_u64 v[4:5], s[6:7], 0, v[134:135]
	global_load_dwordx4 v[204:207], v[2:3], off nt
	global_load_dwordx4 v[208:211], v[4:5], off nt
	v_lshl_add_u64 v[2:3], s[6:7], 0, v[132:133]
	v_lshl_add_u64 v[4:5], s[6:7], 0, v[130:131]
	global_load_dwordx4 v[212:215], v[2:3], off nt
	global_load_dwordx4 v[216:219], v[4:5], off nt
	v_ashrrev_i32_e32 v87, 4, v88
	v_lshlrev_b64 v[2:3], 10, v[162:163]
	v_lshlrev_b32_e32 v4, 3, v87
	v_lshl_add_u64 v[2:3], v[2:3], 1, s[0:1]
	v_ashrrev_i32_e32 v5, 31, v4
	v_lshl_add_u64 v[78:79], v[4:5], 1, v[2:3]
	global_load_dwordx4 v[220:223], v[78:79], off nt
	global_load_dwordx4 v[58:61], v[170:171], off offset:16 nt
	global_load_dwordx4 v[62:65], v[170:171], off nt
	global_load_dwordx4 v[26:29], v[168:169], off offset:16 nt
	global_load_dwordx4 v[30:33], v[168:169], off nt
	global_load_dwordx4 v[50:53], v[170:171], off offset:144 nt
	global_load_dwordx4 v[54:57], v[170:171], off offset:128 nt
	global_load_dwordx4 v[18:21], v[168:169], off offset:144 nt
	global_load_dwordx4 v[22:25], v[168:169], off offset:128 nt
	global_load_dwordx4 v[46:49], v[170:171], off offset:256 nt
	global_load_dwordx4 v[42:45], v[170:171], off offset:272 nt
	global_load_dwordx4 v[10:13], v[168:169], off offset:272 nt
	global_load_dwordx4 v[14:17], v[168:169], off offset:256 nt
	global_load_dwordx4 v[38:41], v[170:171], off offset:384 nt
	global_load_dwordx4 v[34:37], v[170:171], off offset:400 nt
	global_load_dwordx4 v[2:5], v[168:169], off offset:400 nt
	global_load_dwordx4 v[6:9], v[168:169], off offset:384 nt
	global_load_dwordx4 v[224:227], v[78:79], off offset:64 nt
	global_load_dwordx4 v[228:231], v[78:79], off offset:128 nt
	global_load_dwordx4 v[82:85], v[78:79], off offset:192 nt
	global_load_dwordx4 v[74:77], v[78:79], off offset:256 nt
	global_load_dwordx4 v[70:73], v[78:79], off offset:320 nt
	global_load_dwordx4 v[66:69], v[78:79], off offset:384 nt
	s_nop 0
	global_load_dwordx4 v[78:81], v[78:79], off offset:448 nt
	v_lshlrev_b32_e32 v89, 2, v86
	v_and_b32_e32 v88, 3, v88
	v_and_or_b32 v88, v89, 48, v88
	s_waitcnt vmcnt(39)
	ds_write_b128 v172, v[90:93]
	s_waitcnt vmcnt(38)
	ds_write_b128 v173, v[94:97]
	s_waitcnt vmcnt(37)
	ds_write_b128 v174, v[98:101]
	s_waitcnt vmcnt(36)
	ds_write_b128 v175, v[102:105]
	s_waitcnt vmcnt(35)
	ds_write_b128 v176, v[106:109]
	s_waitcnt vmcnt(34)
	ds_write_b128 v177, v[110:113]
	s_waitcnt vmcnt(33)
	ds_write_b128 v178, v[114:117]
	s_waitcnt vmcnt(32)
	ds_write_b128 v179, v[118:121]
	s_waitcnt vmcnt(31)
	ds_write_b128 v180, v[122:125]
	s_waitcnt vmcnt(30)
	ds_write_b128 v181, v[126:129]
	s_waitcnt vmcnt(29)
	ds_write_b128 v182, v[196:199]
	s_waitcnt vmcnt(28)
	ds_write_b128 v183, v[200:203]
	s_waitcnt vmcnt(27)
	ds_write_b128 v184, v[204:207]
	s_waitcnt vmcnt(26)
	ds_write_b128 v185, v[208:211]
	s_waitcnt vmcnt(25)
	ds_write_b128 v186, v[212:215]
	s_waitcnt vmcnt(24)
	ds_write_b128 v187, v[216:219]
	v_lshlrev_b32_e32 v128, 9, v88
	v_xor_b32_e32 v88, v87, v86
	v_lshl_add_u32 v129, v88, 4, 0
	v_or_b32_e32 v195, 0x10000, v128
	v_or_b32_e32 v236, 0x10800, v128
	v_or_b32_e32 v237, 0x11000, v128
	v_or_b32_e32 v238, 0x11800, v128
	v_or_b32_e32 v239, 0x18000, v128
	v_or_b32_e32 v240, 0x18800, v128
	v_or_b32_e32 v241, 0x19000, v128
	v_or_b32_e32 v242, 0x19800, v128
	v_add_u32_e32 v116, v129, v128
	v_add_u32_e32 v120, v129, v195
	v_add_u32_e32 v124, v129, v236
	v_add_u32_e32 v196, v129, v237
	v_add_u32_e32 v200, v129, v238
	v_add_u32_e32 v204, v129, v239
	v_add_u32_e32 v208, v129, v240
	v_add_u32_e32 v212, v129, v241
	v_add_u32_e32 v129, v129, v242
	s_waitcnt lgkmcnt(0)
	s_barrier
; #define LAS __attribute__((address_space(3)))
; #define MFMA16(a, b, c) __builtin_amdgcn_mfma_f32_16x16x32_bf16(a, b, c, 0, 0, 0)
; __device__ __forceinline__ void retC_unit(Frame& F, int unit) {
;     ...
; #pragma unroll
;         for (int s = 0; s < 8; ++s) {
; #pragma unroll
;             for (int j = 0; j < 16; ++j) { const bf16x8 aa = *(const LAS bf16x8*)(F.lds + (64 * (j >> 2) + 16 * (fr >> 2) + 4 * (j & 3) + (fr & 3)) * 512 + (((4 * s + fq) ^ fr) * 16)); acc[j] = MFMA16(aa, qf[s], acc[j]); }
;         }
	ds_read_b128 v[88:91], v116
	ds_read_b128 v[92:95], v116 offset:2048
	ds_read_b128 v[96:99], v116 offset:4096
	ds_read_b128 v[100:103], v116 offset:6144
	ds_read_b128 v[104:107], v116 offset:32768
	ds_read_b128 v[108:111], v116 offset:34816
	ds_read_b128 v[112:115], v116 offset:36864
	ds_read_b128 v[116:119], v116 offset:38912
	ds_read_b128 v[120:123], v120
	ds_read_b128 v[124:127], v124
	ds_read_b128 v[196:199], v196
	ds_read_b128 v[216:219], v129
	ds_read_b128 v[200:203], v200
	ds_read_b128 v[204:207], v204
	ds_read_b128 v[208:211], v208
	ds_read_b128 v[212:215], v212
	v_add_u32_e32 v129, 4, v87
	v_xor_b32_e32 v129, v129, v86
	v_lshl_add_u32 v129, v129, 4, 0
	v_add_u32_e32 v243, v129, v128
	s_waitcnt vmcnt(23) lgkmcnt(14)
	v_mfma_f32_16x16x32_bf16 v[88:91], v[88:91], v[220:223], 0
	ds_read_b128 v[232:235], v243
	v_mfma_f32_16x16x32_bf16 v[92:95], v[92:95], v[220:223], 0
	s_waitcnt lgkmcnt(14)
	v_mfma_f32_16x16x32_bf16 v[96:99], v[96:99], v[220:223], 0
	s_waitcnt lgkmcnt(13)
	v_mfma_f32_16x16x32_bf16 v[100:103], v[100:103], v[220:223], 0
	s_waitcnt lgkmcnt(12)
	v_mfma_f32_16x16x32_bf16 v[104:107], v[104:107], v[220:223], 0
	s_waitcnt lgkmcnt(11)
	v_mfma_f32_16x16x32_bf16 v[108:111], v[108:111], v[220:223], 0
	s_waitcnt lgkmcnt(10)
	v_mfma_f32_16x16x32_bf16 v[112:115], v[112:115], v[220:223], 0
	s_waitcnt lgkmcnt(9)
	v_mfma_f32_16x16x32_bf16 v[116:119], v[116:119], v[220:223], 0
	s_waitcnt lgkmcnt(8)
	v_mfma_f32_16x16x32_bf16 v[120:123], v[120:123], v[220:223], 0
	s_waitcnt lgkmcnt(7)
	v_mfma_f32_16x16x32_bf16 v[124:127], v[124:127], v[220:223], 0
	s_waitcnt lgkmcnt(6)
	v_mfma_f32_16x16x32_bf16 v[196:199], v[196:199], v[220:223], 0
	s_waitcnt lgkmcnt(4)
	v_mfma_f32_16x16x32_bf16 v[200:203], v[200:203], v[220:223], 0
	s_waitcnt lgkmcnt(3)
	v_mfma_f32_16x16x32_bf16 v[204:207], v[204:207], v[220:223], 0
	s_waitcnt lgkmcnt(2)
	v_mfma_f32_16x16x32_bf16 v[208:211], v[208:211], v[220:223], 0
	s_waitcnt lgkmcnt(1)
	v_mfma_f32_16x16x32_bf16 v[212:215], v[212:215], v[220:223], 0
	v_mfma_f32_16x16x32_bf16 v[216:219], v[216:219], v[220:223], 0
	ds_read_b128 v[220:223], v243 offset:2048
	s_waitcnt vmcnt(6) lgkmcnt(1)
	v_mfma_f32_16x16x32_bf16 v[88:91], v[232:235], v[224:227], v[88:91]
	ds_read_b128 v[232:235], v243 offset:4096
	s_waitcnt lgkmcnt(1)
	v_mfma_f32_16x16x32_bf16 v[92:95], v[220:223], v[224:227], v[92:95]
	ds_read_b128 v[220:223], v243 offset:6144
	s_waitcnt lgkmcnt(1)
	v_mfma_f32_16x16x32_bf16 v[96:99], v[232:235], v[224:227], v[96:99]
	ds_read_b128 v[232:235], v243 offset:32768
	s_waitcnt lgkmcnt(1)
	v_mfma_f32_16x16x32_bf16 v[100:103], v[220:223], v[224:227], v[100:103]
	ds_read_b128 v[220:223], v243 offset:34816
	s_waitcnt lgkmcnt(1)
	v_mfma_f32_16x16x32_bf16 v[104:107], v[232:235], v[224:227], v[104:107]
	ds_read_b128 v[232:235], v243 offset:36864
	s_waitcnt lgkmcnt(1)
	v_mfma_f32_16x16x32_bf16 v[108:111], v[220:223], v[224:227], v[108:111]
	ds_read_b128 v[220:223], v243 offset:38912
	s_waitcnt lgkmcnt(1)
	v_mfma_f32_16x16x32_bf16 v[112:115], v[232:235], v[224:227], v[112:115]
	v_add_u32_e32 v232, v129, v195
	ds_read_b128 v[232:235], v232
	s_waitcnt lgkmcnt(1)
	v_mfma_f32_16x16x32_bf16 v[116:119], v[220:223], v[224:227], v[116:119]
	v_add_u32_e32 v220, v129, v236
	ds_read_b128 v[220:223], v220
	s_waitcnt lgkmcnt(1)
	v_mfma_f32_16x16x32_bf16 v[120:123], v[232:235], v[224:227], v[120:123]
	v_add_u32_e32 v232, v129, v237
	ds_read_b128 v[232:235], v232
	s_waitcnt lgkmcnt(1)
	v_mfma_f32_16x16x32_bf16 v[124:127], v[220:223], v[224:227], v[124:127]
	v_add_u32_e32 v220, v129, v238
	ds_read_b128 v[220:223], v220
	s_waitcnt lgkmcnt(1)
	v_mfma_f32_16x16x32_bf16 v[196:199], v[232:235], v[224:227], v[196:199]
	v_add_u32_e32 v232, v129, v239
	ds_read_b128 v[232:235], v232
	s_waitcnt lgkmcnt(1)
	v_mfma_f32_16x16x32_bf16 v[200:203], v[220:223], v[224:227], v[200:203]
	v_add_u32_e32 v220, v129, v240
	ds_read_b128 v[220:223], v220
	s_waitcnt lgkmcnt(0)
	v_mfma_f32_16x16x32_bf16 v[208:211], v[220:223], v[224:227], v[208:211]
	v_add_u32_e32 v220, v129, v241
	ds_read_b128 v[220:223], v220
	v_add_u32_e32 v129, v129, v242
	v_mfma_f32_16x16x32_bf16 v[204:207], v[232:235], v[224:227], v[204:207]
	ds_read_b128 v[232:235], v129
	v_add_u32_e32 v129, 8, v87
	v_xor_b32_e32 v129, v129, v86
	v_lshl_add_u32 v129, v129, 4, 0
	v_add_u32_e32 v243, v129, v128
	s_waitcnt lgkmcnt(1)
	v_mfma_f32_16x16x32_bf16 v[212:215], v[220:223], v[224:227], v[212:215]
	ds_read_b128 v[220:223], v243
	s_waitcnt lgkmcnt(1)
	v_mfma_f32_16x16x32_bf16 v[216:219], v[232:235], v[224:227], v[216:219]
	ds_read_b128 v[224:227], v243 offset:2048
	s_waitcnt vmcnt(5) lgkmcnt(1)
	v_mfma_f32_16x16x32_bf16 v[88:91], v[220:223], v[228:231], v[88:91]
	ds_read_b128 v[220:223], v243 offset:4096
	s_waitcnt lgkmcnt(1)
	v_mfma_f32_16x16x32_bf16 v[92:95], v[224:227], v[228:231], v[92:95]
	ds_read_b128 v[224:227], v243 offset:6144
	s_waitcnt lgkmcnt(1)
	v_mfma_f32_16x16x32_bf16 v[96:99], v[220:223], v[228:231], v[96:99]
	ds_read_b128 v[220:223], v243 offset:32768
	s_waitcnt lgkmcnt(1)
	v_mfma_f32_16x16x32_bf16 v[100:103], v[224:227], v[228:231], v[100:103]
	ds_read_b128 v[224:227], v243 offset:34816
	s_waitcnt lgkmcnt(1)
	v_mfma_f32_16x16x32_bf16 v[104:107], v[220:223], v[228:231], v[104:107]
	ds_read_b128 v[220:223], v243 offset:36864
	s_waitcnt lgkmcnt(1)
	v_mfma_f32_16x16x32_bf16 v[108:111], v[224:227], v[228:231], v[108:111]
	ds_read_b128 v[224:227], v243 offset:38912
	s_waitcnt lgkmcnt(1)
	v_mfma_f32_16x16x32_bf16 v[112:115], v[220:223], v[228:231], v[112:115]
	v_add_u32_e32 v220, v129, v195
	ds_read_b128 v[220:223], v220
	s_waitcnt lgkmcnt(1)
; #define LAS __attribute__((address_space(3)))
; #define MFMA16(a, b, c) __builtin_amdgcn_mfma_f32_16x16x32_bf16(a, b, c, 0, 0, 0)
; __device__ __forceinline__ void retC_unit(Frame& F, int unit) {
;     ...
; #pragma unroll
;         for (int s = 0; s < 8; ++s) {
; #pragma unroll
;             for (int j = 0; j < 16; ++j) { const bf16x8 aa = *(const LAS bf16x8*)(F.lds + (64 * (j >> 2) + 16 * (fr >> 2) + 4 * (j & 3) + (fr & 3)) * 512 + (((4 * s + fq) ^ fr) * 16)); acc[j] = MFMA16(aa, qf[s], acc[j]); }
;         }
	v_mfma_f32_16x16x32_bf16 v[116:119], v[224:227], v[228:231], v[116:119]
	v_add_u32_e32 v224, v129, v236
	ds_read_b128 v[224:227], v224
	s_waitcnt lgkmcnt(1)
	v_mfma_f32_16x16x32_bf16 v[120:123], v[220:223], v[228:231], v[120:123]
	v_add_u32_e32 v220, v129, v237
	ds_read_b128 v[220:223], v220
	s_waitcnt lgkmcnt(1)
	v_mfma_f32_16x16x32_bf16 v[124:127], v[224:227], v[228:231], v[124:127]
	v_add_u32_e32 v224, v129, v238
	ds_read_b128 v[224:227], v224
	s_waitcnt lgkmcnt(1)
	v_mfma_f32_16x16x32_bf16 v[196:199], v[220:223], v[228:231], v[196:199]
	v_add_u32_e32 v220, v129, v239
	ds_read_b128 v[220:223], v220
	s_waitcnt lgkmcnt(1)
	v_mfma_f32_16x16x32_bf16 v[200:203], v[224:227], v[228:231], v[200:203]
	v_add_u32_e32 v224, v129, v240
	ds_read_b128 v[224:227], v224
	s_waitcnt lgkmcnt(1)
	v_mfma_f32_16x16x32_bf16 v[204:207], v[220:223], v[228:231], v[204:207]
	v_add_u32_e32 v220, v129, v241
	ds_read_b128 v[220:223], v220
	v_add_u32_e32 v129, v129, v242
	s_waitcnt lgkmcnt(1)
	v_mfma_f32_16x16x32_bf16 v[208:211], v[224:227], v[228:231], v[208:211]
	ds_read_b128 v[224:227], v129
	v_add_u32_e32 v129, 12, v87
	v_xor_b32_e32 v129, v129, v86
	v_lshl_add_u32 v129, v129, 4, 0
	v_add_u32_e32 v232, v129, v128
	s_waitcnt lgkmcnt(1)
	v_mfma_f32_16x16x32_bf16 v[212:215], v[220:223], v[228:231], v[212:215]
	ds_read_b128 v[220:223], v232
	s_waitcnt lgkmcnt(1)
	v_mfma_f32_16x16x32_bf16 v[216:219], v[224:227], v[228:231], v[216:219]
	ds_read_b128 v[224:227], v232 offset:2048
	s_waitcnt vmcnt(4) lgkmcnt(1)
	v_mfma_f32_16x16x32_bf16 v[88:91], v[220:223], v[82:85], v[88:91]
	ds_read_b128 v[220:223], v232 offset:4096
	s_waitcnt lgkmcnt(1)
	v_mfma_f32_16x16x32_bf16 v[92:95], v[224:227], v[82:85], v[92:95]
	ds_read_b128 v[224:227], v232 offset:6144
	s_waitcnt lgkmcnt(1)
	v_mfma_f32_16x16x32_bf16 v[96:99], v[220:223], v[82:85], v[96:99]
	ds_read_b128 v[220:223], v232 offset:32768
	s_waitcnt lgkmcnt(1)
	v_mfma_f32_16x16x32_bf16 v[100:103], v[224:227], v[82:85], v[100:103]
	ds_read_b128 v[224:227], v232 offset:34816
	s_waitcnt lgkmcnt(1)
	v_mfma_f32_16x16x32_bf16 v[104:107], v[220:223], v[82:85], v[104:107]
	ds_read_b128 v[220:223], v232 offset:36864
	s_waitcnt lgkmcnt(1)
	v_mfma_f32_16x16x32_bf16 v[108:111], v[224:227], v[82:85], v[108:111]
	ds_read_b128 v[224:227], v232 offset:38912
	s_waitcnt lgkmcnt(1)
	v_mfma_f32_16x16x32_bf16 v[112:115], v[220:223], v[82:85], v[112:115]
	v_add_u32_e32 v220, v129, v195
	ds_read_b128 v[220:223], v220
	s_waitcnt lgkmcnt(1)
	v_mfma_f32_16x16x32_bf16 v[116:119], v[224:227], v[82:85], v[116:119]
	v_add_u32_e32 v224, v129, v236
	ds_read_b128 v[224:227], v224
	s_waitcnt lgkmcnt(1)
	v_mfma_f32_16x16x32_bf16 v[120:123], v[220:223], v[82:85], v[120:123]
	v_add_u32_e32 v220, v129, v237
	ds_read_b128 v[220:223], v220
	s_waitcnt lgkmcnt(1)
	v_mfma_f32_16x16x32_bf16 v[124:127], v[224:227], v[82:85], v[124:127]
	v_add_u32_e32 v224, v129, v238
	ds_read_b128 v[224:227], v224
	s_waitcnt lgkmcnt(1)
	v_mfma_f32_16x16x32_bf16 v[196:199], v[220:223], v[82:85], v[196:199]
	v_add_u32_e32 v220, v129, v239
	ds_read_b128 v[220:223], v220
	s_waitcnt lgkmcnt(1)
	v_mfma_f32_16x16x32_bf16 v[200:203], v[224:227], v[82:85], v[200:203]
	v_add_u32_e32 v224, v129, v240
	ds_read_b128 v[224:227], v224
	s_waitcnt lgkmcnt(1)
	v_mfma_f32_16x16x32_bf16 v[204:207], v[220:223], v[82:85], v[204:207]
	v_add_u32_e32 v220, v129, v241
	v_add_u32_e32 v129, v129, v242
	ds_read_b128 v[220:223], v220
	s_waitcnt lgkmcnt(1)
	v_mfma_f32_16x16x32_bf16 v[208:211], v[224:227], v[82:85], v[208:211]
	ds_read_b128 v[224:227], v129
	v_add_u32_e32 v129, 16, v87
	v_xor_b32_e32 v129, v129, v86
	v_lshl_add_u32 v129, v129, 4, 0
	v_add_u32_e32 v228, v129, v128
	s_waitcnt lgkmcnt(1)
	v_mfma_f32_16x16x32_bf16 v[212:215], v[220:223], v[82:85], v[212:215]
	ds_read_b128 v[220:223], v228
	s_waitcnt lgkmcnt(1)
	v_mfma_f32_16x16x32_bf16 v[82:85], v[224:227], v[82:85], v[216:219]
	s_nop 2
	ds_read_b128 v[216:219], v228 offset:2048
	s_waitcnt vmcnt(3) lgkmcnt(1)
	v_mfma_f32_16x16x32_bf16 v[88:91], v[220:223], v[74:77], v[88:91]
	ds_read_b128 v[220:223], v228 offset:4096
	s_waitcnt lgkmcnt(1)
	v_mfma_f32_16x16x32_bf16 v[92:95], v[216:219], v[74:77], v[92:95]
	ds_read_b128 v[216:219], v228 offset:6144
	s_waitcnt lgkmcnt(1)
	v_mfma_f32_16x16x32_bf16 v[96:99], v[220:223], v[74:77], v[96:99]
	ds_read_b128 v[220:223], v228 offset:32768
	s_waitcnt lgkmcnt(1)
	v_mfma_f32_16x16x32_bf16 v[100:103], v[216:219], v[74:77], v[100:103]
	ds_read_b128 v[216:219], v228 offset:34816
	s_waitcnt lgkmcnt(1)
	v_mfma_f32_16x16x32_bf16 v[104:107], v[220:223], v[74:77], v[104:107]
	ds_read_b128 v[220:223], v228 offset:36864
	s_waitcnt lgkmcnt(1)
	v_mfma_f32_16x16x32_bf16 v[108:111], v[216:219], v[74:77], v[108:111]
	ds_read_b128 v[216:219], v228 offset:38912
	s_waitcnt lgkmcnt(1)
	v_mfma_f32_16x16x32_bf16 v[112:115], v[220:223], v[74:77], v[112:115]
	v_add_u32_e32 v220, v129, v195
	ds_read_b128 v[220:223], v220
	s_waitcnt lgkmcnt(1)
	v_mfma_f32_16x16x32_bf16 v[116:119], v[216:219], v[74:77], v[116:119]
	v_add_u32_e32 v216, v129, v236
	ds_read_b128 v[216:219], v216
	s_waitcnt lgkmcnt(1)
	v_mfma_f32_16x16x32_bf16 v[120:123], v[220:223], v[74:77], v[120:123]
	v_add_u32_e32 v220, v129, v237
	ds_read_b128 v[220:223], v220
	s_waitcnt lgkmcnt(1)
	v_mfma_f32_16x16x32_bf16 v[124:127], v[216:219], v[74:77], v[124:127]
	v_add_u32_e32 v216, v129, v238
	ds_read_b128 v[216:219], v216
	s_waitcnt lgkmcnt(1)
	v_mfma_f32_16x16x32_bf16 v[196:199], v[220:223], v[74:77], v[196:199]
	v_add_u32_e32 v220, v129, v239
	ds_read_b128 v[220:223], v220
	s_waitcnt lgkmcnt(1)
	v_mfma_f32_16x16x32_bf16 v[200:203], v[216:219], v[74:77], v[200:203]
	v_add_u32_e32 v216, v129, v240
	ds_read_b128 v[216:219], v216
	s_waitcnt lgkmcnt(0)
; #define LAS __attribute__((address_space(3)))
; #define MFMA16(a, b, c) __builtin_amdgcn_mfma_f32_16x16x32_bf16(a, b, c, 0, 0, 0)
; __device__ __forceinline__ void retC_unit(Frame& F, int unit) {
;     ...
; #pragma unroll
;         for (int s = 0; s < 8; ++s) {
; #pragma unroll
;             for (int j = 0; j < 16; ++j) { const bf16x8 aa = *(const LAS bf16x8*)(F.lds + (64 * (j >> 2) + 16 * (fr >> 2) + 4 * (j & 3) + (fr & 3)) * 512 + (((4 * s + fq) ^ fr) * 16)); acc[j] = MFMA16(aa, qf[s], acc[j]); }
;         }
	v_mfma_f32_16x16x32_bf16 v[208:211], v[216:219], v[74:77], v[208:211]
	v_add_u32_e32 v216, v129, v241
	v_add_u32_e32 v129, v129, v242
	ds_read_b128 v[216:219], v216
	v_mfma_f32_16x16x32_bf16 v[204:207], v[220:223], v[74:77], v[204:207]
	ds_read_b128 v[220:223], v129
	v_add_u32_e32 v129, 20, v87
	v_xor_b32_e32 v129, v129, v86
	v_lshl_add_u32 v129, v129, 4, 0
	v_add_u32_e32 v224, v129, v128
	s_waitcnt lgkmcnt(1)
	v_mfma_f32_16x16x32_bf16 v[212:215], v[216:219], v[74:77], v[212:215]
	ds_read_b128 v[216:219], v224
	s_waitcnt lgkmcnt(1)
	v_mfma_f32_16x16x32_bf16 v[74:77], v[220:223], v[74:77], v[82:85]
	s_nop 2
	ds_read_b128 v[82:85], v224 offset:2048
	s_waitcnt vmcnt(2) lgkmcnt(1)
	v_mfma_f32_16x16x32_bf16 v[88:91], v[216:219], v[70:73], v[88:91]
	ds_read_b128 v[216:219], v224 offset:4096
	s_waitcnt lgkmcnt(1)
	v_mfma_f32_16x16x32_bf16 v[82:85], v[82:85], v[70:73], v[92:95]
	s_nop 2
	ds_read_b128 v[92:95], v224 offset:6144
	s_waitcnt lgkmcnt(1)
	v_mfma_f32_16x16x32_bf16 v[96:99], v[216:219], v[70:73], v[96:99]
	ds_read_b128 v[216:219], v224 offset:32768
	s_waitcnt lgkmcnt(1)
	v_mfma_f32_16x16x32_bf16 v[92:95], v[92:95], v[70:73], v[100:103]
	s_nop 2
	ds_read_b128 v[100:103], v224 offset:34816
	s_waitcnt lgkmcnt(1)
	v_mfma_f32_16x16x32_bf16 v[104:107], v[216:219], v[70:73], v[104:107]
	ds_read_b128 v[216:219], v224 offset:36864
	s_waitcnt lgkmcnt(1)
	v_mfma_f32_16x16x32_bf16 v[100:103], v[100:103], v[70:73], v[108:111]
	s_nop 2
	ds_read_b128 v[108:111], v224 offset:38912
	s_waitcnt lgkmcnt(1)
	v_mfma_f32_16x16x32_bf16 v[112:115], v[216:219], v[70:73], v[112:115]
	v_add_u32_e32 v216, v129, v195
	ds_read_b128 v[216:219], v216
	s_waitcnt lgkmcnt(1)
	v_mfma_f32_16x16x32_bf16 v[108:111], v[108:111], v[70:73], v[116:119]
	s_nop 2
	v_add_u32_e32 v116, v129, v236
	ds_read_b128 v[116:119], v116
	s_waitcnt lgkmcnt(1)
	v_mfma_f32_16x16x32_bf16 v[120:123], v[216:219], v[70:73], v[120:123]
	v_add_u32_e32 v216, v129, v237
	ds_read_b128 v[216:219], v216
	s_waitcnt lgkmcnt(1)
	v_mfma_f32_16x16x32_bf16 v[116:119], v[116:119], v[70:73], v[124:127]
	s_nop 2
	v_add_u32_e32 v124, v129, v238
	ds_read_b128 v[124:127], v124
	s_waitcnt lgkmcnt(1)
	v_mfma_f32_16x16x32_bf16 v[196:199], v[216:219], v[70:73], v[196:199]
	v_add_u32_e32 v216, v129, v239
	ds_read_b128 v[216:219], v216
	s_waitcnt lgkmcnt(1)
	v_mfma_f32_16x16x32_bf16 v[124:127], v[124:127], v[70:73], v[200:203]
	s_nop 2
	v_add_u32_e32 v200, v129, v240
	ds_read_b128 v[200:203], v200
	s_waitcnt lgkmcnt(0)
	v_mfma_f32_16x16x32_bf16 v[200:203], v[200:203], v[70:73], v[208:211]
	s_nop 2
	v_add_u32_e32 v208, v129, v241
	v_add_u32_e32 v129, v129, v242
	ds_read_b128 v[208:211], v208
	v_mfma_f32_16x16x32_bf16 v[204:207], v[216:219], v[70:73], v[204:207]
	ds_read_b128 v[216:219], v129
	v_add_u32_e32 v129, 24, v87
	v_xor_b32_e32 v129, v129, v86
	v_lshl_add_u32 v129, v129, 4, 0
	v_add_u32_e32 v220, v129, v128
	s_waitcnt lgkmcnt(1)
	v_mfma_f32_16x16x32_bf16 v[208:211], v[208:211], v[70:73], v[212:215]
	v_add_u32_e32 v87, 28, v87
	s_nop 1
	ds_read_b128 v[212:215], v220
	v_xor_b32_e32 v86, v87, v86
	s_waitcnt lgkmcnt(1)
	v_mfma_f32_16x16x32_bf16 v[70:73], v[216:219], v[70:73], v[74:77]
	v_lshl_add_u32 v243, v86, 4, 0
	v_add_u32_e32 v86, v243, v128
	s_nop 0
	ds_read_b128 v[74:77], v220 offset:2048
	s_waitcnt vmcnt(1) lgkmcnt(1)
	v_mfma_f32_16x16x32_bf16 v[88:91], v[212:215], v[66:69], v[88:91]
	ds_read_b128 v[212:215], v220 offset:4096
	s_waitcnt lgkmcnt(1)
	v_mfma_f32_16x16x32_bf16 v[74:77], v[74:77], v[66:69], v[82:85]
	s_nop 2
	ds_read_b128 v[82:85], v220 offset:6144
	s_waitcnt lgkmcnt(1)
	v_mfma_f32_16x16x32_bf16 v[96:99], v[212:215], v[66:69], v[96:99]
	ds_read_b128 v[212:215], v220 offset:32768
	s_waitcnt lgkmcnt(1)
	v_mfma_f32_16x16x32_bf16 v[82:85], v[82:85], v[66:69], v[92:95]
	s_nop 2
	ds_read_b128 v[92:95], v220 offset:34816
	s_waitcnt lgkmcnt(1)
; #define LAS __attribute__((address_space(3)))
; #define MFMA16(a, b, c) __builtin_amdgcn_mfma_f32_16x16x32_bf16(a, b, c, 0, 0, 0)
; __device__ __forceinline__ void retC_unit(Frame& F, int unit) {
;     ...
; #pragma unroll
;         for (int s = 0; s < 8; ++s) {
; #pragma unroll
;             for (int j = 0; j < 16; ++j) { const bf16x8 aa = *(const LAS bf16x8*)(F.lds + (64 * (j >> 2) + 16 * (fr >> 2) + 4 * (j & 3) + (fr & 3)) * 512 + (((4 * s + fq) ^ fr) * 16)); acc[j] = MFMA16(aa, qf[s], acc[j]); }
;         }
	v_mfma_f32_16x16x32_bf16 v[104:107], v[212:215], v[66:69], v[104:107]
	ds_read_b128 v[212:215], v220 offset:36864
	s_waitcnt lgkmcnt(1)
	v_mfma_f32_16x16x32_bf16 v[92:95], v[92:95], v[66:69], v[100:103]
	s_nop 2
	ds_read_b128 v[100:103], v220 offset:38912
	s_waitcnt lgkmcnt(0)
	v_mfma_f32_16x16x32_bf16 v[216:219], v[100:103], v[66:69], v[108:111]
	v_add_u32_e32 v100, v129, v236
	ds_read_b128 v[100:103], v100
	s_nop 0
	v_add_u32_e32 v108, v129, v237
	ds_read_b128 v[108:111], v108
	s_waitcnt lgkmcnt(1)
	v_mfma_f32_16x16x32_bf16 v[224:227], v[100:103], v[66:69], v[116:119]
	v_add_u32_e32 v100, v129, v238
	ds_read_b128 v[100:103], v100
	s_waitcnt lgkmcnt(1)
	v_mfma_f32_16x16x32_bf16 v[196:199], v[108:111], v[66:69], v[196:199]
	v_add_u32_e32 v108, v129, v239
	ds_read_b128 v[108:111], v108
	s_waitcnt lgkmcnt(1)
	v_mfma_f32_16x16x32_bf16 v[228:231], v[100:103], v[66:69], v[124:127]
	v_add_u32_e32 v100, v129, v240
	ds_read_b128 v[100:103], v100
	s_waitcnt lgkmcnt(1)
	v_mfma_f32_16x16x32_bf16 v[204:207], v[108:111], v[66:69], v[204:207]
	v_add_u32_e32 v108, v129, v242
	ds_read_b128 v[108:111], v108
	v_mfma_f32_16x16x32_bf16 v[212:215], v[212:215], v[66:69], v[112:115]
	s_nop 2
	v_add_u32_e32 v112, v129, v195
	s_waitcnt lgkmcnt(1)
	v_mfma_f32_16x16x32_bf16 v[200:203], v[100:103], v[66:69], v[200:203]
	v_add_u32_e32 v100, v129, v241
	ds_read_b128 v[112:115], v112
	ds_read_b128 v[100:103], v100
	s_waitcnt lgkmcnt(1)
	v_mfma_f32_16x16x32_bf16 v[220:223], v[112:115], v[66:69], v[120:123]
	s_waitcnt lgkmcnt(0)
	v_mfma_f32_16x16x32_bf16 v[208:211], v[100:103], v[66:69], v[208:211]
	ds_read_b128 v[100:103], v86
	v_mfma_f32_16x16x32_bf16 v[232:235], v[108:111], v[66:69], v[70:73]
	ds_read_b128 v[66:69], v86 offset:2048
	s_nop 1
	ds_read_b128 v[70:73], v86 offset:4096
	s_waitcnt vmcnt(0) lgkmcnt(1)
	v_mfma_f32_16x16x32_bf16 v[126:129], v[66:69], v[78:81], v[74:77]
	ds_read_b128 v[66:69], v86 offset:6144
	s_waitcnt lgkmcnt(1)
	v_mfma_f32_16x16x32_bf16 v[122:125], v[70:73], v[78:81], v[96:99]
	ds_read_b128 v[70:73], v86 offset:32768
	s_waitcnt lgkmcnt(1)
	v_mfma_f32_16x16x32_bf16 v[118:121], v[66:69], v[78:81], v[82:85]
	ds_read_b128 v[66:69], v86 offset:34816
	s_waitcnt lgkmcnt(1)
	v_mfma_f32_16x16x32_bf16 v[110:113], v[70:73], v[78:81], v[104:107]
	ds_read_b128 v[70:73], v86 offset:36864
	s_waitcnt lgkmcnt(1)
	v_mfma_f32_16x16x32_bf16 v[106:109], v[66:69], v[78:81], v[92:95]
	ds_read_b128 v[66:69], v86 offset:38912
	v_mfma_f32_16x16x32_bf16 v[114:117], v[100:103], v[78:81], v[88:91]
	s_waitcnt lgkmcnt(1)
	v_mfma_f32_16x16x32_bf16 v[102:105], v[70:73], v[78:81], v[212:215]
	v_add_u32_e32 v70, v243, v195
	ds_read_b128 v[70:73], v70
	s_waitcnt lgkmcnt(1)
	v_mfma_f32_16x16x32_bf16 v[98:101], v[66:69], v[78:81], v[216:219]
	v_add_u32_e32 v66, v243, v236
	ds_read_b128 v[66:69], v66
	s_waitcnt lgkmcnt(1)
	v_mfma_f32_16x16x32_bf16 v[94:97], v[70:73], v[78:81], v[220:223]
	v_add_u32_e32 v70, v243, v237
	ds_read_b128 v[70:73], v70
	s_waitcnt lgkmcnt(1)
	v_mfma_f32_16x16x32_bf16 v[90:93], v[66:69], v[78:81], v[224:227]
	v_add_u32_e32 v66, v243, v238
	ds_read_b128 v[66:69], v66
	s_waitcnt lgkmcnt(1)
	v_mfma_f32_16x16x32_bf16 v[86:89], v[70:73], v[78:81], v[196:199]
	v_add_u32_e32 v70, v243, v239
	ds_read_b128 v[70:73], v70
	s_waitcnt lgkmcnt(1)
	v_mfma_f32_16x16x32_bf16 v[82:85], v[66:69], v[78:81], v[228:231]
	v_add_u32_e32 v66, v243, v240
	ds_read_b128 v[66:69], v66
	s_waitcnt lgkmcnt(1)
	v_mfma_f32_16x16x32_bf16 v[74:77], v[70:73], v[78:81], v[204:207]
	v_add_u32_e32 v70, v243, v241
	ds_read_b128 v[196:199], v70
	s_waitcnt lgkmcnt(1)
	v_mfma_f32_16x16x32_bf16 v[70:73], v[66:69], v[78:81], v[200:203]
	v_add_u32_e32 v66, v243, v242
	s_nop 1
	ds_read_b128 v[200:203], v66
	s_waitcnt lgkmcnt(1)
	v_mfma_f32_16x16x32_bf16 v[66:69], v[196:199], v[78:81], v[208:211]
	s_waitcnt lgkmcnt(0)
	v_mfma_f32_16x16x32_bf16 v[78:81], v[200:203], v[78:81], v[232:235]
	s_lshl_b32 s4, s23, 8
	s_cbranch_execnz .LBB0_1112
	s_branch .LBB0_1111

; template <bool OUT8, int NP, bool S16, bool FIN>
; __device__ __forceinline__ void norm_sample_rows(Frame& F, const float* srcS32, const float* gain, int sub, bf16* Hd, float* yS) {
;     ...
;     for (int hr0 = F.vcu; hr0 < MS; hr0 += 2 * F.G) {
;         const int k = 256 * w + 4 * flane;
;         int hrs[2]; hrs[0] = hr0; hrs[1] = (hr0 + F.G < MS) ? hr0 + F.G : hr0;
;         f32x4 v[2]; f32x4 sv[2][NP > 0 ? NP : 1]; f32x4 g4, s0[2], s1[2], h0[2], h1[2];
; #pragma unroll
;         for (int q = 0; q < 2; ++q) { const int hr = hrs[q], m = MP + hr;
;             v[q] = S16 ? ld4_bf16(X16 + (size_t)m * DM + k) : *(const f32x4*)(srcS32 + (size_t)hr * DM + k);
; #pragma unroll
;             for (int p = 0; p < NP; ++p) sv[q][p] = ld4_bf16(slab + ((size_t)p * MS + hr) * DM + k); }
;         g4 = *(const f32x4*)(gain + k);
;         if (!FIN) {
; #pragma unroll
;             for (int q = 0; q < 2; ++q) { const float* sh = WSP(float, WS_MODS) + (size_t)pg8::modrow_of(MP + hrs[q]) * NMOD + (size_t)(3 * sub) * DM; const float* sc = sh + DM;
;                 s0[q] = *(const f32x4*)(sc + k); s1[q] = *(const f32x4*)(sc + MODSB_DELTA + k); h0[q] = *(const f32x4*)(sh + k); h1[q] = *(const f32x4*)(sh + MODSB_DELTA + k); }
;         }
;         float ssw[2];
; #pragma unroll
;         for (int q = 0; q < 2; ++q) {
;             if (NP > 0) {
; #pragma unroll
;                 for (int p = 0; p < NP; ++p) v[q] += sv[q][p];
.LBB0_1567:
	s_nop 0
	v_lshl_add_u64 v[0:1], s[14:15], 0, v[4:5]
	global_load_dwordx2 v[2:3], v[0:1], off nt
	v_lshl_add_u64 v[16:17], s[10:11], 0, v[4:5]
	v_add_co_u32_e32 v0, vcc, s7, v16
	s_add_i32 s2, s94, s43
	s_nop 0
	v_addc_co_u32_e32 v1, vcc, 0, v17, vcc
	global_load_dwordx2 v[18:19], v[0:1], off nt
	v_add_co_u32_e32 v0, vcc, s20, v16
	s_cmpk_lt_i32 s2, 0x200
	s_nop 0
	v_addc_co_u32_e32 v1, vcc, 0, v17, vcc
	global_load_dwordx2 v[20:21], v[0:1], off nt
	v_add_co_u32_e32 v0, vcc, s21, v16
	s_cselect_b32 s16, s2, s43
	s_nop 0
	v_addc_co_u32_e32 v1, vcc, 0, v17, vcc
	v_add_co_u32_e32 v22, vcc, s22, v16
	global_load_dwordx2 v[0:1], v[0:1], off nt
	s_nop 0
	v_addc_co_u32_e32 v23, vcc, 0, v17, vcc
	v_add_co_u32_e32 v34, vcc, s23, v16
	global_load_dwordx2 v[22:23], v[22:23], off nt
	s_nop 0
	v_addc_co_u32_e32 v35, vcc, 0, v17, vcc
	v_add_co_u32_e32 v36, vcc, s24, v16
	s_ashr_i32 s17, s16, 31
	s_nop 0
	v_addc_co_u32_e32 v37, vcc, 0, v17, vcc
	v_add_co_u32_e32 v38, vcc, s25, v16
	s_lshl_b64 s[2:3], s[16:17], 12
	s_nop 0
	v_addc_co_u32_e32 v39, vcc, 0, v17, vcc
	v_add_co_u32_e32 v40, vcc, s26, v16
	v_lshl_add_u64 v[56:57], v[8:9], 0, s[2:3]
	s_nop 0
	v_addc_co_u32_e32 v41, vcc, 0, v17, vcc
	v_add_co_u32_e32 v42, vcc, s27, v16
	global_load_dwordx2 v[34:35], v[34:35], off nt
	s_nop 0
	global_load_dwordx2 v[44:45], v[36:37], off nt
	global_load_dwordx2 v[46:47], v[38:39], off nt
	global_load_dwordx2 v[48:49], v[40:41], off nt
	v_addc_co_u32_e32 v43, vcc, 0, v17, vcc
	v_add_co_u32_e32 v36, vcc, s28, v16
	s_waitcnt vmcnt(7)
	v_lshlrev_b32_e32 v50, 16, v18
	v_addc_co_u32_e32 v37, vcc, 0, v17, vcc
	v_add_co_u32_e32 v16, vcc, s29, v16
	v_and_b32_e32 v51, 0xffff0000, v18
	s_nop 0
	v_addc_co_u32_e32 v17, vcc, 0, v17, vcc
	global_load_dwordx2 v[38:39], v[42:43], off nt
	global_load_dwordx2 v[40:41], v[36:37], off nt
	s_nop 0
	global_load_dwordx2 v[42:43], v[16:17], off nt
	v_lshlrev_b32_e32 v16, 16, v2
	v_and_b32_e32 v17, 0xffff0000, v2
	v_lshlrev_b32_e32 v36, 16, v3
	v_and_b32_e32 v37, 0xffff0000, v3
	v_lshl_add_u64 v[2:3], v[6:7], 0, s[2:3]
	v_add_co_u32_e32 v2, vcc, s30, v2
	s_waitcnt vmcnt(8)
	v_lshlrev_b32_e32 v54, 16, v0
	v_addc_co_u32_e32 v3, vcc, 0, v3, vcc
	v_add_co_u32_e32 v58, vcc, s31, v56
	v_and_b32_e32 v55, 0xffff0000, v0
	s_nop 0
	v_addc_co_u32_e32 v59, vcc, 0, v57, vcc
	v_add_co_u32_e32 v60, vcc, s33, v56
	v_lshlrev_b32_e32 v78, 16, v1
	s_nop 0
	v_addc_co_u32_e32 v61, vcc, 0, v57, vcc
	global_load_dwordx2 v[2:3], v[2:3], off nt
	s_nop 0
	global_load_dwordx2 v[62:63], v[56:57], off nt
	global_load_dwordx2 v[64:65], v[58:59], off nt
	global_load_dwordx2 v[66:67], v[60:61], off nt
	v_add_co_u32_e32 v58, vcc, s34, v56
	v_and_b32_e32 v79, 0xffff0000, v1
	s_nop 0
	v_addc_co_u32_e32 v59, vcc, 0, v57, vcc
	v_add_co_u32_e32 v60, vcc, s35, v56
	global_load_dwordx2 v[58:59], v[58:59], off nt
	s_nop 0
	v_addc_co_u32_e32 v61, vcc, 0, v57, vcc
	v_add_co_u32_e32 v68, vcc, s36, v56
	v_lshlrev_b32_e32 v18, 16, v19
	s_nop 0
	v_addc_co_u32_e32 v69, vcc, 0, v57, vcc
	v_add_co_u32_e32 v70, vcc, s37, v56
	v_and_b32_e32 v19, 0xffff0000, v19
	s_nop 0
	v_addc_co_u32_e32 v71, vcc, 0, v57, vcc
	global_load_dwordx2 v[60:61], v[60:61], off nt
	s_nop 0
	global_load_dwordx2 v[72:73], v[68:69], off nt
	global_load_dwordx2 v[74:75], v[70:71], off nt
	v_add_co_u32_e32 v68, vcc, s38, v56
	v_lshlrev_b32_e32 v52, 16, v20
	s_nop 0
	v_addc_co_u32_e32 v69, vcc, 0, v57, vcc
	v_add_co_u32_e32 v70, vcc, s39, v56
	v_and_b32_e32 v53, 0xffff0000, v20
	s_nop 0
	v_addc_co_u32_e32 v71, vcc, 0, v57, vcc
	v_add_co_u32_e32 v76, vcc, s40, v56
	global_load_dwordx2 v[68:69], v[68:69], off nt
	s_nop 0
	global_load_dwordx2 v[70:71], v[70:71], off nt
	v_addc_co_u32_e32 v77, vcc, 0, v57, vcc
	v_add_co_u32_e32 v56, vcc, s41, v56
	global_load_dwordx2 v[76:77], v[76:77], off nt
	s_nop 0
	v_addc_co_u32_e32 v57, vcc, 0, v57, vcc
	global_load_dwordx2 v[56:57], v[56:57], off nt
	v_lshlrev_b32_e32 v20, 16, v21
	v_and_b32_e32 v21, 0xffff0000, v21
	v_pk_add_f32 v[18:19], v[36:37], v[18:19]
	v_pk_add_f32 v[16:17], v[16:17], v[50:51]
	v_pk_add_f32 v[18:19], v[18:19], v[20:21]
	v_pk_add_f32 v[16:17], v[16:17], v[52:53]
	s_waitcnt vmcnt(19)
	v_lshlrev_b32_e32 v80, 16, v22
	v_and_b32_e32 v81, 0xffff0000, v22
	v_lshlrev_b32_e32 v22, 16, v23
	v_and_b32_e32 v23, 0xffff0000, v23
	v_pk_add_f32 v[18:19], v[18:19], v[78:79]
	v_pk_add_f32 v[16:17], v[16:17], v[54:55]
	s_waitcnt vmcnt(18)
	v_lshlrev_b32_e32 v82, 16, v34
	v_and_b32_e32 v83, 0xffff0000, v34
	v_lshlrev_b32_e32 v34, 16, v35
	v_and_b32_e32 v35, 0xffff0000, v35
	v_pk_add_f32 v[16:17], v[16:17], v[80:81]
	v_pk_add_f32 v[18:19], v[18:19], v[22:23]
	s_waitcnt vmcnt(17)
	v_lshlrev_b32_e32 v84, 16, v44
	v_and_b32_e32 v85, 0xffff0000, v44
	v_lshlrev_b32_e32 v44, 16, v45
	v_and_b32_e32 v45, 0xffff0000, v45
	v_pk_add_f32 v[18:19], v[18:19], v[34:35]
	v_pk_add_f32 v[16:17], v[16:17], v[82:83]
	s_waitcnt vmcnt(16)
	v_lshlrev_b32_e32 v86, 16, v46
	v_and_b32_e32 v87, 0xffff0000, v46
	v_lshlrev_b32_e32 v46, 16, v47
	v_and_b32_e32 v47, 0xffff0000, v47
	v_pk_add_f32 v[16:17], v[16:17], v[84:85]
	v_pk_add_f32 v[18:19], v[18:19], v[44:45]
	s_waitcnt vmcnt(15)
	v_lshlrev_b32_e32 v90, 16, v48
	v_and_b32_e32 v91, 0xffff0000, v48
	v_lshlrev_b32_e32 v48, 16, v49
	v_and_b32_e32 v49, 0xffff0000, v49
	s_waitcnt vmcnt(11)
; #define GAS __attribute__((address_space(1)))
; __device__ __forceinline__ unsigned pk2(float lo, float hi) { return f2bf(lo) | (f2bf(hi) << 16); }
; template <bool OUT8, int NP, bool S16, bool FIN>
; __device__ __forceinline__ void norm_sample_rows(Frame& F, const float* srcS32, const float* gain, int sub, bf16* Hd, float* yS) {
;     ...
; #pragma unroll
;         for (int q = 0; q < 2; ++q) {
;             if (NP > 0) {
; #pragma unroll
;                 for (int p = 0; p < NP; ++p) v[q] += sv[q][p];
;                 if (!FIN) { v2u pk; pk.x = pk2(v[q][0], v[q][1]); pk.y = pk2(v[q][2], v[q][3]); *(GAS v2u*)(X16 + (size_t)(MP + hrs[q]) * DM + k) = pk; }
;             }
;             ssw[q] = wave_sum((v[q][0] * v[q][0] + v[q][1] * v[q][1]) + (v[q][2] * v[q][2] + v[q][3] * v[q][3]));
;         }
;         if (flane == 0) { part[par * 16 + w] = ssw[0]; part[par * 16 + 8 + w] = ssw[1]; }
;         __syncthreads();
	v_lshlrev_b32_e32 v98, 16, v2
	v_and_b32_e32 v99, 0xffff0000, v2
	v_lshlrev_b32_e32 v100, 16, v3
	v_and_b32_e32 v101, 0xffff0000, v3
	global_load_dwordx4 v[0:3], v[10:11], off nt
	v_pk_add_f32 v[18:19], v[18:19], v[46:47]
	v_pk_add_f32 v[16:17], v[16:17], v[86:87]
	v_lshlrev_b32_e32 v92, 16, v38
	v_and_b32_e32 v93, 0xffff0000, v38
	v_lshlrev_b32_e32 v38, 16, v39
	v_and_b32_e32 v39, 0xffff0000, v39
	v_pk_add_f32 v[16:17], v[16:17], v[90:91]
	v_pk_add_f32 v[18:19], v[18:19], v[48:49]
	v_lshlrev_b32_e32 v94, 16, v40
	v_and_b32_e32 v95, 0xffff0000, v40
	v_lshlrev_b32_e32 v40, 16, v41
	v_and_b32_e32 v41, 0xffff0000, v41
	v_pk_add_f32 v[18:19], v[18:19], v[38:39]
	v_pk_add_f32 v[16:17], v[16:17], v[92:93]
	v_lshlrev_b32_e32 v96, 16, v42
	v_and_b32_e32 v97, 0xffff0000, v42
	v_lshlrev_b32_e32 v42, 16, v43
	v_and_b32_e32 v43, 0xffff0000, v43
	v_pk_add_f32 v[20:21], v[16:17], v[94:95]
	v_pk_add_f32 v[16:17], v[18:19], v[40:41]
	v_pk_add_f32 v[18:19], v[20:21], v[96:97]
	v_pk_add_f32 v[16:17], v[16:17], v[42:43]
	v_mul_f32_e32 v20, v19, v19
	v_mul_f32_e32 v21, v17, v17
	s_waitcnt vmcnt(11)
	v_lshlrev_b32_e32 v102, 16, v62
	v_and_b32_e32 v103, 0xffff0000, v62
	v_lshlrev_b32_e32 v62, 16, v63
	v_and_b32_e32 v63, 0xffff0000, v63
	v_fmac_f32_e32 v20, v18, v18
	v_fmac_f32_e32 v21, v16, v16
	s_waitcnt vmcnt(10)
	v_lshlrev_b32_e32 v104, 16, v64
	v_and_b32_e32 v105, 0xffff0000, v64
	v_lshlrev_b32_e32 v64, 16, v65
	v_and_b32_e32 v65, 0xffff0000, v65
	v_add_f32_e32 v33, v20, v21
	v_pk_add_f32 v[20:21], v[100:101], v[62:63]
	v_pk_add_f32 v[22:23], v[98:99], v[102:103]
	s_waitcnt vmcnt(9)
	v_lshlrev_b32_e32 v106, 16, v66
	v_and_b32_e32 v107, 0xffff0000, v66
	v_lshlrev_b32_e32 v66, 16, v67
	v_and_b32_e32 v67, 0xffff0000, v67
	v_pk_add_f32 v[22:23], v[22:23], v[104:105]
	v_pk_add_f32 v[20:21], v[20:21], v[64:65]
	s_waitcnt vmcnt(8)
	v_lshlrev_b32_e32 v108, 16, v58
	v_and_b32_e32 v109, 0xffff0000, v58
	v_lshlrev_b32_e32 v58, 16, v59
	v_and_b32_e32 v59, 0xffff0000, v59
	v_pk_add_f32 v[20:21], v[20:21], v[66:67]
	v_pk_add_f32 v[22:23], v[22:23], v[106:107]
	s_waitcnt vmcnt(7)
	v_lshlrev_b32_e32 v110, 16, v60
	v_and_b32_e32 v111, 0xffff0000, v60
	v_lshlrev_b32_e32 v60, 16, v61
	v_and_b32_e32 v61, 0xffff0000, v61
	v_pk_add_f32 v[22:23], v[22:23], v[108:109]
	v_pk_add_f32 v[20:21], v[20:21], v[58:59]
	s_waitcnt vmcnt(6)
	v_lshlrev_b32_e32 v112, 16, v72
	v_and_b32_e32 v113, 0xffff0000, v72
	v_lshlrev_b32_e32 v72, 16, v73
	v_and_b32_e32 v73, 0xffff0000, v73
	v_pk_add_f32 v[20:21], v[20:21], v[60:61]
	v_pk_add_f32 v[22:23], v[22:23], v[110:111]
	s_waitcnt vmcnt(5)
	v_lshlrev_b32_e32 v114, 16, v74
	v_and_b32_e32 v115, 0xffff0000, v74
	v_lshlrev_b32_e32 v74, 16, v75
	v_and_b32_e32 v75, 0xffff0000, v75
	v_pk_add_f32 v[22:23], v[22:23], v[112:113]
	v_pk_add_f32 v[20:21], v[20:21], v[72:73]
	s_waitcnt vmcnt(4)
	v_lshlrev_b32_e32 v116, 16, v68
	v_and_b32_e32 v117, 0xffff0000, v68
	v_lshlrev_b32_e32 v68, 16, v69
	v_and_b32_e32 v69, 0xffff0000, v69
	v_pk_add_f32 v[20:21], v[20:21], v[74:75]
	v_pk_add_f32 v[22:23], v[22:23], v[114:115]
	s_waitcnt vmcnt(3)
	v_lshlrev_b32_e32 v118, 16, v70
	v_and_b32_e32 v119, 0xffff0000, v70
	v_lshlrev_b32_e32 v70, 16, v71
	v_and_b32_e32 v71, 0xffff0000, v71
	v_pk_add_f32 v[22:23], v[22:23], v[116:117]
	v_pk_add_f32 v[20:21], v[20:21], v[68:69]
	s_waitcnt vmcnt(2)
	v_lshlrev_b32_e32 v120, 16, v76
	v_and_b32_e32 v121, 0xffff0000, v76
	v_lshlrev_b32_e32 v76, 16, v77
	v_and_b32_e32 v77, 0xffff0000, v77
	v_pk_add_f32 v[20:21], v[20:21], v[70:71]
	v_pk_add_f32 v[22:23], v[22:23], v[118:119]
	s_waitcnt vmcnt(1)
	v_lshlrev_b32_e32 v122, 16, v56
	v_and_b32_e32 v123, 0xffff0000, v56
	v_lshlrev_b32_e32 v56, 16, v57
	v_and_b32_e32 v57, 0xffff0000, v57
	v_pk_add_f32 v[22:23], v[22:23], v[120:121]
	v_pk_add_f32 v[20:21], v[20:21], v[76:77]
	v_pk_add_f32 v[22:23], v[22:23], v[122:123]
	v_pk_add_f32 v[20:21], v[20:21], v[56:57]
	v_mul_f32_e32 v35, v23, v23
	v_mul_f32_e32 v36, v21, v21
	v_fmac_f32_e32 v35, v22, v22
	v_fmac_f32_e32 v36, v20, v20
	v_add_f32_e32 v35, v35, v36
	ds_bpermute_b32 v34, v25, v33
	ds_bpermute_b32 v36, v25, v35
	s_waitcnt lgkmcnt(1)
	v_add_f32_e32 v33, v33, v34
	s_waitcnt lgkmcnt(0)
	v_add_f32_e32 v35, v35, v36
	ds_bpermute_b32 v34, v26, v33
	ds_bpermute_b32 v36, v26, v35
	s_waitcnt lgkmcnt(1)
	v_add_f32_e32 v33, v33, v34
	s_waitcnt lgkmcnt(0)
	v_add_f32_e32 v35, v35, v36
	ds_bpermute_b32 v34, v27, v33
	ds_bpermute_b32 v36, v27, v35
	s_waitcnt lgkmcnt(1)
	v_add_f32_e32 v33, v33, v34
	s_waitcnt lgkmcnt(0)
	v_add_f32_e32 v35, v35, v36
	ds_bpermute_b32 v34, v28, v33
	ds_bpermute_b32 v36, v28, v35
	s_waitcnt lgkmcnt(1)
	v_add_f32_e32 v33, v33, v34
	s_waitcnt lgkmcnt(0)
	v_add_f32_e32 v36, v35, v36
	ds_bpermute_b32 v34, v29, v33
	ds_bpermute_b32 v37, v29, v36
	s_waitcnt lgkmcnt(1)
	v_add_f32_e32 v33, v33, v34
	s_waitcnt lgkmcnt(0)
	v_add_f32_e32 v34, v36, v37
	ds_bpermute_b32 v35, v30, v33
	ds_bpermute_b32 v36, v30, v34
	s_and_saveexec_b64 s[2:3], s[0:1]
	s_xor_b64 s[2:3], exec, s[2:3]
	s_lshl_b32 s44, s18, 6
	s_or_saveexec_b64 s[2:3], s[2:3]
	v_mov_b32_e32 v37, s44
	s_xor_b64 exec, exec, s[2:3]
	s_cbranch_execz .LBB0_1566
	s_lshl_b32 s44, s18, 6
	s_add_i32 s45, s19, s44
	s_waitcnt lgkmcnt(0)
	v_add_f32_e32 v34, v34, v36
	v_add_f32_e32 v33, v33, v35
	v_mov_b32_e32 v35, s45
	v_mov_b32_e32 v37, s44
	ds_write2_b32 v35, v33, v34 offset1:8
	s_branch .LBB0_1566

; #define LAS __attribute__((address_space(3)))
; template <int OUTM, bool P16>
; __device__ __forceinline__ void norm_prompt_rows(Frame& F, const float* srcP32, const float* gain, int sub, bf16* Hd, float* yP) {
;     ...
;     for (int mb = 32 * F.vcu; mb < MP; mb += 32 * F.G) {
;         const int m0 = mb + 4 * F.wave;
;         int flane = flane0; asm volatile("" : "+v"(flane));
;         v4u raw[P16 ? RB : 1][4]; f32x4 vf[P16 ? 1 : RB][4][2];
; #pragma unroll
;         for (int r = 0; r < RB; ++r) NPR_LOAD(r, m0 + r);
;         f32x4 Am[4][2], Bm[4][2];
;         if (OUTM == 2) {
; #pragma unroll
;             for (int j = 0; j < 4; ++j)
; #pragma unroll
;                 for (int hf = 0; hf < 2; ++hf) { Am[j][hf] = *(const f32x4*)(gain + 8 * (flane + 64 * j) + 4 * hf); Bm[j][hf] = (f32x4){0.f, 0.f, 0.f, 0.f}; }
;         } else {
;             { const int k = 4 * (64 * F.wave + flane);
;                 const float* sh = WSP(float, WS_MODS) + (size_t)pg8::modrow_of(mb) * NMOD + (size_t)(3 * sub) * DM; const float* sc = sh + DM;
;                 const f32x4 g4 = *(const f32x4*)(gain + k), s0 = *(const f32x4*)(sc + k), s1 = *(const f32x4*)(sc + MODSB_DELTA + k), h0 = *(const f32x4*)(sh + k), h1 = *(const f32x4*)(sh + MODSB_DELTA + k);
;                 *(LAS f32x4*)(modA + k) = g4 * ((s0 + s1) + 1.0f); *(LAS f32x4*)(modB + k) = h0 + h1; }
;             __syncthreads();
; #pragma unroll
;             for (int j = 0; j < 4; ++j)
; #pragma unroll
;                 for (int hf = 0; hf < 2; ++hf) { const int k = 8 * (flane + 64 * j) + 4 * hf; Am[j][hf] = *(const LAS f32x4*)(modA + k); Bm[j][hf] = *(const LAS f32x4*)(modB + k); }
;         }
; #pragma unroll
;         for (int r = 0; r < 4; ++r) {
;             const int slot = r % RB;
;             float ss = 0.f;
; #pragma unroll
;             for (int j = 0; j < 4; ++j) { f32x4 x0, x1; NPR_GET(slot, j, x0, x1);
;                 ss += ((x0[0] * x0[0] + x0[1] * x0[1]) + (x0[2] * x0[2] + x0[3] * x0[3])) + ((x1[0] * x1[0] + x1[1] * x1[1]) + (x1[2] * x1[2] + x1[3] * x1[3])); }
;             const float rstd = 1.0f / sqrtf(wave_sum(ss) * (1.0f / DM) + EPS);
.LBB0_1573:
	s_add_i32 s10, s13, s12
	v_mov_b32_e32 v0, v88
	s_ashr_i32 s11, s10, 31
	s_lshl_b64 s[0:1], s[10:11], 12
	v_lshlrev_b32_e32 v22, 3, v0
	v_ashrrev_i32_e32 v23, 31, v22
	s_add_u32 s0, s4, s0
	v_add_u32_e32 v86, 0x200, v22
	s_addc_u32 s1, s5, s1
	v_lshlrev_b64 v[24:25], 1, v[22:23]
	v_ashrrev_i32_e32 v87, 31, v86
	v_add_u32_e32 v2, 0x400, v22
	v_lshl_add_u64 v[0:1], s[0:1], 0, v[24:25]
	v_lshlrev_b64 v[26:27], 1, v[86:87]
	v_ashrrev_i32_e32 v3, 31, v2
	global_load_dwordx4 v[6:9], v[0:1], off nt
	v_lshl_add_u64 v[0:1], s[0:1], 0, v[26:27]
	v_lshlrev_b64 v[28:29], 1, v[2:3]
	global_load_dwordx4 v[10:13], v[0:1], off nt
	v_lshl_add_u64 v[0:1], s[0:1], 0, v[28:29]
	global_load_dwordx4 v[14:17], v[0:1], off nt
	v_add_u32_e32 v0, 0x600, v22
	v_ashrrev_i32_e32 v1, 31, v0
	v_lshlrev_b64 v[4:5], 1, v[0:1]
	v_lshl_add_u64 v[18:19], s[0:1], 0, v[4:5]
	global_load_dwordx4 v[18:21], v[18:19], off nt
	v_cmp_lt_i32_e32 vcc, v91, v90
	s_add_i32 s8, s10, 1
	s_ashr_i32 s9, s8, 31
	v_cndmask_b32_e32 v30, v89, v91, vcc
	v_lshlrev_b32_e32 v99, 2, v30
	v_cmp_lt_i32_e32 vcc, v92, v90
	s_lshl_b64 s[0:1], s[8:9], 12
	s_add_u32 s0, s4, s0
	s_addc_u32 s1, s5, s1
	s_add_i32 s6, s10, 2
	s_ashr_i32 s7, s6, 31
	v_lshl_add_u64 v[30:31], s[0:1], 0, v[24:25]
	v_lshl_add_u64 v[32:33], s[0:1], 0, v[26:27]
	v_lshl_add_u64 v[34:35], s[0:1], 0, v[28:29]
	v_lshl_add_u64 v[36:37], s[0:1], 0, v[4:5]
	s_lshl_b64 s[0:1], s[6:7], 12
	s_add_u32 s0, s4, s0
	s_addc_u32 s1, s5, s1
	s_add_i32 s2, s10, 3
	s_ashr_i32 s3, s2, 31
	global_load_dwordx4 v[76:79], v[30:31], off nt
	global_load_dwordx4 v[72:75], v[32:33], off nt
	global_load_dwordx4 v[68:71], v[34:35], off nt
	global_load_dwordx4 v[64:67], v[36:37], off nt
	v_lshl_add_u64 v[30:31], s[0:1], 0, v[24:25]
	v_lshl_add_u64 v[32:33], s[0:1], 0, v[26:27]
	v_lshl_add_u64 v[34:35], s[0:1], 0, v[28:29]
	v_lshl_add_u64 v[36:37], s[0:1], 0, v[4:5]
	s_lshl_b64 s[0:1], s[2:3], 12
	s_add_u32 s0, s4, s0
	v_lshlrev_b64 v[80:81], 2, v[22:23]
	s_addc_u32 s1, s5, s1
	v_lshl_add_u64 v[22:23], s[74:75], 0, v[80:81]
	v_lshl_add_u64 v[24:25], s[0:1], 0, v[24:25]
	v_lshl_add_u64 v[26:27], s[0:1], 0, v[26:27]
	v_lshl_add_u64 v[82:83], s[0:1], 0, v[28:29]
	v_lshl_add_u64 v[4:5], s[0:1], 0, v[4:5]
	global_load_dwordx4 v[60:63], v[30:31], off nt
	global_load_dwordx4 v[56:59], v[32:33], off nt
	global_load_dwordx4 v[52:55], v[34:35], off nt
	global_load_dwordx4 v[48:51], v[36:37], off nt
	s_nop 0
	global_load_dwordx4 v[36:39], v[24:25], off nt
	global_load_dwordx4 v[28:31], v[26:27], off nt
	s_nop 0
	global_load_dwordx4 v[24:27], v[22:23], off offset:16 nt
	global_load_dwordx4 v[32:35], v[22:23], off nt
	v_lshlrev_b64 v[84:85], 2, v[2:3]
	v_lshlrev_b64 v[86:87], 2, v[86:87]
	s_waitcnt vmcnt(15)
	v_and_b32_e32 v109, 0xffff0000, v7
	v_and_b32_e32 v108, 0xffff0000, v6
	v_and_b32_e32 v113, 0xffff0000, v9
	v_and_b32_e32 v112, 0xffff0000, v8
	v_lshlrev_b32_e32 v107, 16, v7
	v_lshlrev_b32_e32 v106, 16, v6
	v_lshlrev_b32_e32 v111, 16, v9
	v_lshlrev_b32_e32 v110, 16, v8
	v_pk_mul_f32 v[6:7], v[108:109], v[108:109]
	v_pk_mul_f32 v[8:9], v[112:113], v[112:113]
	s_waitcnt vmcnt(14)
	v_and_b32_e32 v117, 0xffff0000, v11
	v_and_b32_e32 v116, 0xffff0000, v10
	v_and_b32_e32 v121, 0xffff0000, v13
	v_and_b32_e32 v120, 0xffff0000, v12
	v_pk_fma_f32 v[6:7], v[106:107], v[106:107], v[6:7]
	v_pk_fma_f32 v[8:9], v[110:111], v[110:111], v[8:9]
	s_waitcnt vmcnt(12)
	v_lshlrev_b32_e32 v130, 16, v18
	v_and_b32_e32 v131, 0xffff0000, v18
	v_lshlrev_b32_e32 v115, 16, v11
	v_lshlrev_b32_e32 v114, 16, v10
	v_lshlrev_b32_e32 v119, 16, v13
	v_lshlrev_b32_e32 v118, 16, v12
	v_pk_mul_f32 v[10:11], v[116:117], v[116:117]
	v_pk_mul_f32 v[12:13], v[120:121], v[120:121]
	v_lshlrev_b32_e32 v122, 16, v14
	v_and_b32_e32 v123, 0xffff0000, v14
	v_lshlrev_b32_e32 v124, 16, v15
	v_and_b32_e32 v125, 0xffff0000, v15
	v_mul_f32_e32 v14, v130, v130
	v_mul_f32_e32 v15, v131, v131
	v_pk_add_f32 v[6:7], v[6:7], v[6:7] op_sel:[0,1] op_sel_hi:[1,0]
	v_pk_add_f32 v[8:9], v[8:9], v[8:9] op_sel:[0,1] op_sel_hi:[1,0]
	v_pk_fma_f32 v[10:11], v[114:115], v[114:115], v[10:11]
	v_pk_fma_f32 v[12:13], v[118:119], v[118:119], v[12:13]
	v_lshlrev_b32_e32 v132, 16, v19
	v_and_b32_e32 v133, 0xffff0000, v19
	v_mov_b32_e32 v7, v14
	v_mov_b32_e32 v9, v15
	v_lshlrev_b32_e32 v126, 16, v16
	v_and_b32_e32 v127, 0xffff0000, v16
	v_lshlrev_b32_e32 v128, 16, v17
	v_and_b32_e32 v129, 0xffff0000, v17
	v_mul_f32_e32 v16, v132, v132
	v_mul_f32_e32 v17, v133, v133
	v_pk_add_f32 v[6:7], v[6:7], v[8:9]
	v_pk_add_f32 v[8:9], v[10:11], v[10:11] op_sel:[0,1] op_sel_hi:[1,0]
	v_pk_add_f32 v[10:11], v[12:13], v[12:13] op_sel:[0,1] op_sel_hi:[1,0]
	v_mov_b32_e32 v9, v16
	v_mov_b32_e32 v11, v17
	v_pk_add_f32 v[8:9], v[8:9], v[10:11]
	v_lshlrev_b32_e32 v134, 16, v20
	v_and_b32_e32 v135, 0xffff0000, v20
	v_pk_add_f32 v[6:7], v[6:7], v[8:9]
	v_mul_f32_e32 v8, v123, v123
	v_mul_f32_e32 v10, v125, v125
	v_mul_f32_e32 v18, v134, v134
	v_mul_f32_e32 v19, v135, v135
	v_pk_fma_f32 v[8:9], v[122:123], v[122:123], v[8:9] op_sel_hi:[1,1,0]
	v_pk_fma_f32 v[10:11], v[124:125], v[124:125], v[10:11] op_sel_hi:[1,1,0]
	v_mov_b32_e32 v9, v18
	v_mov_b32_e32 v11, v19
	v_lshlrev_b32_e32 v136, 16, v21
	v_and_b32_e32 v137, 0xffff0000, v21
	v_pk_add_f32 v[8:9], v[8:9], v[10:11]
	v_mul_f32_e32 v10, v127, v127
	v_mul_f32_e32 v12, v129, v129
	v_mul_f32_e32 v20, v136, v136
	v_mul_f32_e32 v21, v137, v137
	v_pk_fma_f32 v[10:11], v[126:127], v[126:127], v[10:11] op_sel_hi:[1,1,0]
	v_pk_fma_f32 v[12:13], v[128:129], v[128:129], v[12:13] op_sel_hi:[1,1,0]
	v_mov_b32_e32 v11, v20
	v_mov_b32_e32 v13, v21
	v_pk_add_f32 v[10:11], v[10:11], v[12:13]
	s_nop 0
	v_pk_add_f32 v[8:9], v[8:9], v[10:11]
	s_nop 0
	v_pk_add_f32 v[6:7], v[6:7], v[8:9]
	v_cndmask_b32_e32 v8, v89, v92, vcc
	v_add_f32_e32 v6, v6, v7
	ds_bpermute_b32 v7, v99, v6
	v_lshlrev_b32_e32 v100, 2, v8
	v_cmp_lt_i32_e32 vcc, v93, v90
	s_waitcnt lgkmcnt(0)
; #define LAS __attribute__((address_space(3)))
; template <int OUTM, bool P16>
; __device__ __forceinline__ void norm_prompt_rows(Frame& F, const float* srcP32, const float* gain, int sub, bf16* Hd, float* yP) {
;     ...
;         f32x4 Am[4][2], Bm[4][2];
;         if (OUTM == 2) {
; #pragma unroll
;             for (int j = 0; j < 4; ++j)
; #pragma unroll
;                 for (int hf = 0; hf < 2; ++hf) { Am[j][hf] = *(const f32x4*)(gain + 8 * (flane + 64 * j) + 4 * hf); Bm[j][hf] = (f32x4){0.f, 0.f, 0.f, 0.f}; }
;         } else {
;             { const int k = 4 * (64 * F.wave + flane);
;                 const float* sh = WSP(float, WS_MODS) + (size_t)pg8::modrow_of(mb) * NMOD + (size_t)(3 * sub) * DM; const float* sc = sh + DM;
;                 const f32x4 g4 = *(const f32x4*)(gain + k), s0 = *(const f32x4*)(sc + k), s1 = *(const f32x4*)(sc + MODSB_DELTA + k), h0 = *(const f32x4*)(sh + k), h1 = *(const f32x4*)(sh + MODSB_DELTA + k);
;                 *(LAS f32x4*)(modA + k) = g4 * ((s0 + s1) + 1.0f); *(LAS f32x4*)(modB + k) = h0 + h1; }
;             __syncthreads();
; #pragma unroll
;             for (int j = 0; j < 4; ++j)
; #pragma unroll
;                 for (int hf = 0; hf < 2; ++hf) { const int k = 8 * (flane + 64 * j) + 4 * hf; Am[j][hf] = *(const LAS f32x4*)(modA + k); Bm[j][hf] = *(const LAS f32x4*)(modB + k); }
;         }
; #pragma unroll
;         for (int r = 0; r < 4; ++r) {
;             const int slot = r % RB;
;             float ss = 0.f;
; #pragma unroll
;             for (int j = 0; j < 4; ++j) { f32x4 x0, x1; NPR_GET(slot, j, x0, x1);
;                 ss += ((x0[0] * x0[0] + x0[1] * x0[1]) + (x0[2] * x0[2] + x0[3] * x0[3])) + ((x1[0] * x1[0] + x1[1] * x1[1]) + (x1[2] * x1[2] + x1[3] * x1[3])); }
;             const float rstd = 1.0f / sqrtf(wave_sum(ss) * (1.0f / DM) + EPS);
; #pragma unroll
;             for (int j = 0; j < 4; ++j) { const size_t o = (size_t)(m0 + r) * DM + 8 * (flane + 64 * j);
;                 f32x4 x0, x1; NPR_GET(slot, j, x0, x1);
;                 const f32x4 o0 = (x0 * rstd) * Am[j][0] + Bm[j][0], o1 = (x1 * rstd) * Am[j][1] + Bm[j][1];
;                 if (OUTM == 2) { __builtin_nontemporal_store(o0, (f32x4*)(yP + o)); __builtin_nontemporal_store(o1, (f32x4*)(yP + o + 4)); }
	v_add_f32_e32 v6, v6, v7
	ds_bpermute_b32 v7, v100, v6
	v_cndmask_b32_e32 v8, v89, v93, vcc
	v_lshlrev_b32_e32 v101, 2, v8
	v_cmp_lt_i32_e32 vcc, v94, v90
	global_load_dwordx4 v[8:11], v[22:23], off offset:2064 nt
	global_load_dwordx4 v[16:19], v[22:23], off offset:2048 nt
	s_waitcnt lgkmcnt(0)
	v_add_f32_e32 v6, v6, v7
	ds_bpermute_b32 v7, v101, v6
	v_cndmask_b32_e32 v12, v89, v94, vcc
	v_lshlrev_b32_e32 v102, 2, v12
	v_cmp_lt_i32_e32 vcc, v95, v90
	global_load_dwordx4 v[44:47], v[82:83], off nt
	global_load_dwordx4 v[40:43], v[4:5], off nt
	s_waitcnt lgkmcnt(0)
	v_add_f32_e32 v6, v6, v7
	ds_bpermute_b32 v7, v102, v6
	v_cndmask_b32_e32 v4, v89, v95, vcc
	v_lshlrev_b32_e32 v103, 2, v4
	v_cmp_lt_i32_e32 vcc, v96, v90
	v_lshlrev_b64 v[82:83], 2, v[0:1]
	s_waitcnt lgkmcnt(0)
	v_add_f32_e32 v4, v6, v7
	ds_bpermute_b32 v5, v103, v4
	v_cndmask_b32_e32 v2, v89, v96, vcc
	v_lshlrev_b32_e32 v104, 2, v2
	v_lshl_add_u64 v[2:3], s[74:75], 0, v[84:85]
	global_load_dwordx4 v[12:15], v[2:3], off offset:16 nt
	global_load_dwordx4 v[20:23], v[2:3], off nt
	s_waitcnt lgkmcnt(0)
	v_add_f32_e32 v4, v4, v5
	ds_bpermute_b32 v5, v104, v4
	s_waitcnt lgkmcnt(0)
	v_add_f32_e32 v0, v4, v5
	v_fmamk_f32 v0, v0, 0x3a000000, v97
	v_mul_f32_e32 v1, 0x4f800000, v0
	v_cmp_gt_f32_e32 vcc, s15, v0
	v_lshl_add_u64 v[4:5], s[74:75], 0, v[82:83]
	s_nop 0
	v_cndmask_b32_e32 v105, v0, v1, vcc
	global_load_dwordx4 v[0:3], v[4:5], off offset:16 nt
	s_nop 0
	global_load_dwordx4 v[4:7], v[4:5], off nt
	v_sqrt_f32_e32 v138, v105
	s_nop 0
	v_add_u32_e32 v139, -1, v138
	v_fma_f32 v140, -v139, v138, v105
	v_cmp_ge_f32_e64 s[0:1], 0, v140
	v_add_u32_e32 v140, 1, v138
	s_nop 0
	v_cndmask_b32_e64 v139, v138, v139, s[0:1]
	v_fma_f32 v138, -v140, v138, v105
	v_cmp_lt_f32_e64 s[0:1], 0, v138
	s_nop 1
	v_cndmask_b32_e64 v138, v139, v140, s[0:1]
	v_mul_f32_e32 v139, 0x37800000, v138
	v_cndmask_b32_e32 v138, v138, v139, vcc
	v_cmp_class_f32_e32 vcc, v105, v98
	s_nop 1
	v_cndmask_b32_e32 v105, v138, v105, vcc
	v_div_scale_f32 v138, s[0:1], v105, v105, 1.0
	v_rcp_f32_e32 v139, v138
	s_lshl_b64 s[0:1], s[10:11], 13
	s_add_u32 s0, s76, s0
	s_addc_u32 s1, s77, s1
	v_fma_f32 v140, -v138, v139, 1.0
	v_fmac_f32_e32 v139, v140, v139
	v_div_scale_f32 v140, vcc, 1.0, v105, 1.0
	v_mul_f32_e32 v141, v140, v139
	v_fma_f32 v142, -v138, v141, v140
	v_fmac_f32_e32 v141, v142, v139
	v_fma_f32 v138, -v138, v141, v140
	v_div_fmas_f32 v138, v138, v139, v141
	v_div_fixup_f32 v138, v138, v105, 1.0
	v_mov_b32_e32 v140, v106
	v_mov_b32_e32 v141, v108
	v_mov_b32_e32 v108, v107
	v_pk_mul_f32 v[140:141], v[138:139], v[140:141] op_sel_hi:[0,1]
	v_pk_mul_f32 v[106:107], v[138:139], v[108:109] op_sel_hi:[0,1]
	s_waitcnt vmcnt(8)
	v_pk_fma_f32 v[108:109], v[34:35], v[106:107], 0 op_sel_hi:[1,1,0]
	v_pk_fma_f32 v[106:107], v[32:33], v[140:141], 0 op_sel_hi:[1,1,0]
	v_mov_b32_e32 v140, v110
	v_mov_b32_e32 v141, v112
	v_mov_b32_e32 v112, v111
	v_pk_mul_f32 v[140:141], v[138:139], v[140:141] op_sel_hi:[0,1]
	v_pk_mul_f32 v[110:111], v[138:139], v[112:113] op_sel_hi:[0,1]
	v_pk_fma_f32 v[112:113], v[26:27], v[110:111], 0 op_sel_hi:[1,1,0]
	v_pk_fma_f32 v[110:111], v[24:25], v[140:141], 0 op_sel_hi:[1,1,0]
	v_lshl_add_u64 v[140:141], s[0:1], 0, v[80:81]
	global_store_dwordx4 v[140:141], v[106:109], off nt
	global_store_dwordx4 v[140:141], v[110:113], off offset:16 nt
	s_nop 0
	v_mov_b32_e32 v106, v114
	v_mov_b32_e32 v107, v116
	v_mov_b32_e32 v116, v115
	v_pk_mul_f32 v[106:107], v[138:139], v[106:107] op_sel_hi:[0,1]
	v_pk_mul_f32 v[108:109], v[138:139], v[116:117] op_sel_hi:[0,1]
	v_mov_b32_e32 v110, v118
	v_mov_b32_e32 v111, v120
	v_mov_b32_e32 v120, v119
	s_waitcnt vmcnt(8)
	v_pk_fma_f32 v[108:109], v[18:19], v[108:109], 0 op_sel_hi:[1,1,0]
	v_pk_fma_f32 v[106:107], v[16:17], v[106:107], 0 op_sel_hi:[1,1,0]
	v_pk_mul_f32 v[110:111], v[138:139], v[110:111] op_sel_hi:[0,1]
	v_pk_mul_f32 v[112:113], v[138:139], v[120:121] op_sel_hi:[0,1]
	v_lshl_add_u64 v[114:115], s[0:1], 0, v[86:87]
	v_pk_fma_f32 v[112:113], v[10:11], v[112:113], 0 op_sel_hi:[1,1,0]
	v_pk_fma_f32 v[110:111], v[8:9], v[110:111], 0 op_sel_hi:[1,1,0]
	global_store_dwordx4 v[114:115], v[106:109], off nt
	global_store_dwordx4 v[114:115], v[110:113], off offset:16 nt
	v_lshl_add_u64 v[114:115], s[0:1], 0, v[84:85]
	v_pk_mul_f32 v[106:107], v[138:139], v[122:123] op_sel_hi:[0,1]
	v_pk_mul_f32 v[108:109], v[138:139], v[124:125] op_sel_hi:[0,1]
	s_waitcnt vmcnt(6)
	v_pk_fma_f32 v[108:109], v[22:23], v[108:109], 0 op_sel_hi:[1,1,0]
	v_pk_fma_f32 v[106:107], v[20:21], v[106:107], 0 op_sel_hi:[1,1,0]
	v_pk_mul_f32 v[110:111], v[138:139], v[126:127] op_sel_hi:[0,1]
	v_pk_mul_f32 v[112:113], v[138:139], v[128:129] op_sel_hi:[0,1]
	v_pk_fma_f32 v[112:113], v[14:15], v[112:113], 0 op_sel_hi:[1,1,0]
	v_pk_fma_f32 v[110:111], v[12:13], v[110:111], 0 op_sel_hi:[1,1,0]
	global_store_dwordx4 v[114:115], v[106:109], off nt
	global_store_dwordx4 v[114:115], v[110:113], off offset:16 nt
	v_lshl_add_u64 v[114:115], s[0:1], 0, v[82:83]
	v_pk_mul_f32 v[106:107], v[138:139], v[130:131] op_sel_hi:[0,1]
	v_pk_mul_f32 v[108:109], v[138:139], v[132:133] op_sel_hi:[0,1]
	s_waitcnt vmcnt(6)
; template <int OUTM, bool P16>
; __device__ __forceinline__ void norm_prompt_rows(Frame& F, const float* srcP32, const float* gain, int sub, bf16* Hd, float* yP) {
;     ...
;         for (int r = 0; r < 4; ++r) {
;             const int slot = r % RB;
;             float ss = 0.f;
; #pragma unroll
;             for (int j = 0; j < 4; ++j) { f32x4 x0, x1; NPR_GET(slot, j, x0, x1);
;                 ss += ((x0[0] * x0[0] + x0[1] * x0[1]) + (x0[2] * x0[2] + x0[3] * x0[3])) + ((x1[0] * x1[0] + x1[1] * x1[1]) + (x1[2] * x1[2] + x1[3] * x1[3])); }
;             const float rstd = 1.0f / sqrtf(wave_sum(ss) * (1.0f / DM) + EPS);
; #pragma unroll
;             for (int j = 0; j < 4; ++j) { const size_t o = (size_t)(m0 + r) * DM + 8 * (flane + 64 * j);
;                 f32x4 x0, x1; NPR_GET(slot, j, x0, x1);
;                 const f32x4 o0 = (x0 * rstd) * Am[j][0] + Bm[j][0], o1 = (x1 * rstd) * Am[j][1] + Bm[j][1];
;                 if (OUTM == 2) { __builtin_nontemporal_store(o0, (f32x4*)(yP + o)); __builtin_nontemporal_store(o1, (f32x4*)(yP + o + 4)); }
	v_pk_fma_f32 v[108:109], v[6:7], v[108:109], 0 op_sel_hi:[1,1,0]
	v_pk_fma_f32 v[106:107], v[4:5], v[106:107], 0 op_sel_hi:[1,1,0]
	v_pk_mul_f32 v[110:111], v[138:139], v[134:135] op_sel_hi:[0,1]
	v_pk_mul_f32 v[112:113], v[138:139], v[136:137] op_sel_hi:[0,1]
	v_pk_fma_f32 v[112:113], v[2:3], v[112:113], 0 op_sel_hi:[1,1,0]
	v_pk_fma_f32 v[110:111], v[0:1], v[110:111], 0 op_sel_hi:[1,1,0]
	global_store_dwordx4 v[114:115], v[106:109], off nt
	global_store_dwordx4 v[114:115], v[110:113], off offset:16 nt
	s_nop 0
	v_lshlrev_b32_e32 v107, 16, v77
	v_lshlrev_b32_e32 v106, 16, v76
	v_and_b32_e32 v77, 0xffff0000, v77
	v_and_b32_e32 v76, 0xffff0000, v76
	v_pk_mul_f32 v[108:109], v[76:77], v[76:77]
	v_lshlrev_b32_e32 v111, 16, v79
	v_lshlrev_b32_e32 v110, 16, v78
	v_and_b32_e32 v79, 0xffff0000, v79
	v_and_b32_e32 v78, 0xffff0000, v78
	v_pk_fma_f32 v[108:109], v[106:107], v[106:107], v[108:109]
	v_pk_mul_f32 v[112:113], v[78:79], v[78:79]
	v_lshlrev_b32_e32 v130, 16, v64
	v_pk_fma_f32 v[112:113], v[110:111], v[110:111], v[112:113]
	v_lshlrev_b32_e32 v115, 16, v73
	v_lshlrev_b32_e32 v114, 16, v72
	v_and_b32_e32 v73, 0xffff0000, v73
	v_and_b32_e32 v72, 0xffff0000, v72
	v_and_b32_e32 v131, 0xffff0000, v64
	v_lshlrev_b32_e32 v132, 16, v65
	v_and_b32_e32 v133, 0xffff0000, v65
	v_lshlrev_b32_e32 v134, 16, v66
	v_and_b32_e32 v135, 0xffff0000, v66
	v_mul_f32_e32 v66, v130, v130
	v_pk_add_f32 v[64:65], v[108:109], v[108:109] op_sel:[0,1] op_sel_hi:[1,0]
	v_pk_mul_f32 v[116:117], v[72:73], v[72:73]
	v_lshlrev_b32_e32 v119, 16, v75
	v_lshlrev_b32_e32 v118, 16, v74
	v_and_b32_e32 v75, 0xffff0000, v75
	v_and_b32_e32 v74, 0xffff0000, v74
	v_lshlrev_b32_e32 v122, 16, v68
	v_and_b32_e32 v123, 0xffff0000, v68
	v_lshlrev_b32_e32 v136, 16, v67
	v_and_b32_e32 v137, 0xffff0000, v67
	v_mul_f32_e32 v68, v131, v131
	v_mov_b32_e32 v65, v66
	v_pk_add_f32 v[66:67], v[112:113], v[112:113] op_sel:[0,1] op_sel_hi:[1,0]
	v_pk_fma_f32 v[116:117], v[114:115], v[114:115], v[116:117]
	v_pk_mul_f32 v[120:121], v[74:75], v[74:75]
	v_mov_b32_e32 v67, v68
	v_pk_fma_f32 v[120:121], v[118:119], v[118:119], v[120:121]
	v_lshlrev_b32_e32 v124, 16, v69
	v_and_b32_e32 v125, 0xffff0000, v69
	v_mul_f32_e32 v69, v132, v132
	v_pk_add_f32 v[64:65], v[64:65], v[66:67]
	v_pk_add_f32 v[66:67], v[116:117], v[116:117] op_sel:[0,1] op_sel_hi:[1,0]
	v_lshlrev_b32_e32 v126, 16, v70
	v_and_b32_e32 v127, 0xffff0000, v70
	v_mul_f32_e32 v70, v133, v133
	v_mov_b32_e32 v67, v69
	v_pk_add_f32 v[68:69], v[120:121], v[120:121] op_sel:[0,1] op_sel_hi:[1,0]
	v_lshlrev_b32_e32 v128, 16, v71
	v_mov_b32_e32 v69, v70
	v_pk_add_f32 v[66:67], v[66:67], v[68:69]
	v_mul_f32_e32 v68, v125, v125
	v_pk_add_f32 v[64:65], v[64:65], v[66:67]
	v_mul_f32_e32 v66, v123, v123
	v_and_b32_e32 v129, 0xffff0000, v71
	v_mul_f32_e32 v71, v134, v134
	v_mul_f32_e32 v105, v135, v135
	v_pk_fma_f32 v[66:67], v[122:123], v[122:123], v[66:67] op_sel_hi:[1,1,0]
	v_pk_fma_f32 v[68:69], v[124:125], v[124:125], v[68:69] op_sel_hi:[1,1,0]
	v_mov_b32_e32 v67, v71
	v_mov_b32_e32 v69, v105
	v_pk_add_f32 v[66:67], v[66:67], v[68:69]
	v_mul_f32_e32 v68, v127, v127
	v_mul_f32_e32 v70, v129, v129
	v_mul_f32_e32 v138, v136, v136
	v_mul_f32_e32 v139, v137, v137
	v_pk_fma_f32 v[68:69], v[126:127], v[126:127], v[68:69] op_sel_hi:[1,1,0]
	v_pk_fma_f32 v[70:71], v[128:129], v[128:129], v[70:71] op_sel_hi:[1,1,0]
	v_mov_b32_e32 v69, v138
	v_mov_b32_e32 v71, v139
	v_pk_add_f32 v[68:69], v[68:69], v[70:71]
	s_nop 0
	v_pk_add_f32 v[66:67], v[66:67], v[68:69]
	s_nop 0
	v_pk_add_f32 v[64:65], v[64:65], v[66:67]
	s_nop 0
	v_add_f32_e32 v64, v64, v65
	ds_bpermute_b32 v65, v99, v64
	s_waitcnt lgkmcnt(0)
	v_add_f32_e32 v64, v64, v65
	ds_bpermute_b32 v65, v100, v64
	s_waitcnt lgkmcnt(0)
	v_add_f32_e32 v64, v64, v65
	ds_bpermute_b32 v65, v101, v64
	s_waitcnt lgkmcnt(0)
	v_add_f32_e32 v64, v64, v65
	ds_bpermute_b32 v65, v102, v64
	s_waitcnt lgkmcnt(0)
	v_add_f32_e32 v64, v64, v65
	ds_bpermute_b32 v65, v103, v64
	s_waitcnt lgkmcnt(0)
	v_add_f32_e32 v64, v64, v65
	ds_bpermute_b32 v65, v104, v64
	s_waitcnt lgkmcnt(0)
	v_add_f32_e32 v64, v64, v65
	v_fmamk_f32 v64, v64, 0x3a000000, v97
	v_mul_f32_e32 v65, 0x4f800000, v64
	v_cmp_gt_f32_e32 vcc, s15, v64
	s_nop 1
	v_cndmask_b32_e32 v64, v64, v65, vcc
	v_sqrt_f32_e32 v65, v64
	s_nop 0
	v_add_u32_e32 v66, -1, v65
	v_fma_f32 v67, -v66, v65, v64
	v_cmp_ge_f32_e64 s[0:1], 0, v67
	v_add_u32_e32 v67, 1, v65
	s_nop 0
	v_cndmask_b32_e64 v66, v65, v66, s[0:1]
	v_fma_f32 v65, -v67, v65, v64
	v_cmp_lt_f32_e64 s[0:1], 0, v65
	s_nop 1
	v_cndmask_b32_e64 v65, v66, v67, s[0:1]
	v_mul_f32_e32 v66, 0x37800000, v65
	v_cndmask_b32_e32 v65, v65, v66, vcc
	v_cmp_class_f32_e32 vcc, v64, v98
	s_nop 1
	v_cndmask_b32_e32 v64, v65, v64, vcc
	v_div_scale_f32 v65, s[0:1], v64, v64, 1.0
	v_rcp_f32_e32 v66, v65
	s_lshl_b64 s[0:1], s[8:9], 13
	s_add_u32 s0, s76, s0
	s_addc_u32 s1, s77, s1
	v_fma_f32 v67, -v65, v66, 1.0
	v_fmac_f32_e32 v66, v67, v66
	v_div_scale_f32 v67, vcc, 1.0, v64, 1.0
	v_mul_f32_e32 v68, v67, v66
	v_fma_f32 v69, -v65, v68, v67
	v_fmac_f32_e32 v68, v69, v66
	v_fma_f32 v65, -v65, v68, v67
	v_div_fmas_f32 v65, v65, v66, v68
	v_div_fixup_f32 v108, v65, v64, 1.0
	v_mov_b32_e32 v64, v106
	v_mov_b32_e32 v65, v76
	v_mov_b32_e32 v76, v107
	v_pk_mul_f32 v[64:65], v[108:109], v[64:65] op_sel_hi:[0,1]
	v_pk_mul_f32 v[66:67], v[108:109], v[76:77] op_sel_hi:[0,1]
	v_mov_b32_e32 v68, v110
	v_mov_b32_e32 v69, v78
	v_mov_b32_e32 v78, v111
	v_pk_fma_f32 v[66:67], v[34:35], v[66:67], 0 op_sel_hi:[1,1,0]
	v_pk_fma_f32 v[64:65], v[32:33], v[64:65], 0 op_sel_hi:[1,1,0]
	v_pk_mul_f32 v[68:69], v[108:109], v[68:69] op_sel_hi:[0,1]
; #define GAS __attribute__((address_space(1)))
; __device__ __forceinline__ unsigned pk2(float lo, float hi) { return f2bf(lo) | (f2bf(hi) << 16); }
; #define NPR_LOAD(slot, row) do { _Pragma("unroll") for (int j = 0; j < 4; ++j) { const size_t o = (size_t)(row) * DM + 8 * (flane + 64 * j); \
;             if (P16) raw[P16 ? (slot) : 0][j] = *(const v4u*)(X16 + o); \
;             else { vf[P16 ? 0 : (slot)][j][0] = *(const f32x4*)(srcP32 + o); vf[P16 ? 0 : (slot)][j][1] = *(const f32x4*)(srcP32 + o + 4); } } } while (0)
; template <int OUTM, bool P16>
; __device__ __forceinline__ void norm_prompt_rows(Frame& F, const float* srcP32, const float* gain, int sub, bf16* Hd, float* yP) {
;     ...
;         for (int r = 0; r < 4; ++r) {
;             const int slot = r % RB;
;             float ss = 0.f;
; #pragma unroll
;             for (int j = 0; j < 4; ++j) { f32x4 x0, x1; NPR_GET(slot, j, x0, x1);
;                 ss += ((x0[0] * x0[0] + x0[1] * x0[1]) + (x0[2] * x0[2] + x0[3] * x0[3])) + ((x1[0] * x1[0] + x1[1] * x1[1]) + (x1[2] * x1[2] + x1[3] * x1[3])); }
;             const float rstd = 1.0f / sqrtf(wave_sum(ss) * (1.0f / DM) + EPS);
; #pragma unroll
;             for (int j = 0; j < 4; ++j) { const size_t o = (size_t)(m0 + r) * DM + 8 * (flane + 64 * j);
;                 f32x4 x0, x1; NPR_GET(slot, j, x0, x1);
;                 const f32x4 o0 = (x0 * rstd) * Am[j][0] + Bm[j][0], o1 = (x1 * rstd) * Am[j][1] + Bm[j][1];
;                 if (OUTM == 2) { __builtin_nontemporal_store(o0, (f32x4*)(yP + o)); __builtin_nontemporal_store(o1, (f32x4*)(yP + o + 4)); }
;                 else if (OUTM == 1) { v2u pk; pk.x = pg8::pk4_fp8(o0[0], o0[1], o0[2], o0[3]); pk.y = pg8::pk4_fp8(o1[0], o1[1], o1[2], o1[3]); *(GAS v2u*)((unsigned char*)Hd + o) = pk; }
;                 else { v4u pk; pk.x = pk2(o0[0], o0[1]); pk.y = pk2(o0[2], o0[3]); pk.z = pk2(o1[0], o1[1]); pk.w = pk2(o1[2], o1[3]); *(GAS v4u*)(Hd + o) = pk; } }
;             if (r + RB < 4) NPR_LOAD(slot, m0 + r + RB);
;             __builtin_amdgcn_sched_barrier(0);
;         }
	v_pk_mul_f32 v[70:71], v[108:109], v[78:79] op_sel_hi:[0,1]
	v_lshl_add_u64 v[76:77], s[0:1], 0, v[80:81]
	v_pk_fma_f32 v[70:71], v[26:27], v[70:71], 0 op_sel_hi:[1,1,0]
	v_pk_fma_f32 v[68:69], v[24:25], v[68:69], 0 op_sel_hi:[1,1,0]
	global_store_dwordx4 v[76:77], v[64:67], off nt
	global_store_dwordx4 v[76:77], v[68:71], off offset:16 nt
	s_nop 0
	v_mov_b32_e32 v64, v114
	v_mov_b32_e32 v65, v72
	v_mov_b32_e32 v72, v115
	v_pk_mul_f32 v[64:65], v[108:109], v[64:65] op_sel_hi:[0,1]
	v_pk_mul_f32 v[66:67], v[108:109], v[72:73] op_sel_hi:[0,1]
	v_mov_b32_e32 v68, v118
	v_mov_b32_e32 v69, v74
	v_mov_b32_e32 v74, v119
	v_pk_fma_f32 v[66:67], v[18:19], v[66:67], 0 op_sel_hi:[1,1,0]
	v_pk_fma_f32 v[64:65], v[16:17], v[64:65], 0 op_sel_hi:[1,1,0]
	v_pk_mul_f32 v[68:69], v[108:109], v[68:69] op_sel_hi:[0,1]
	v_pk_mul_f32 v[70:71], v[108:109], v[74:75] op_sel_hi:[0,1]
	v_lshl_add_u64 v[72:73], s[0:1], 0, v[86:87]
	v_pk_fma_f32 v[70:71], v[10:11], v[70:71], 0 op_sel_hi:[1,1,0]
	v_pk_fma_f32 v[68:69], v[8:9], v[68:69], 0 op_sel_hi:[1,1,0]
	global_store_dwordx4 v[72:73], v[64:67], off nt
	global_store_dwordx4 v[72:73], v[68:71], off offset:16 nt
	v_lshl_add_u64 v[72:73], s[0:1], 0, v[84:85]
	v_pk_mul_f32 v[64:65], v[108:109], v[122:123] op_sel_hi:[0,1]
	v_pk_mul_f32 v[66:67], v[108:109], v[124:125] op_sel_hi:[0,1]
	v_pk_fma_f32 v[66:67], v[22:23], v[66:67], 0 op_sel_hi:[1,1,0]
	v_pk_fma_f32 v[64:65], v[20:21], v[64:65], 0 op_sel_hi:[1,1,0]
	v_pk_mul_f32 v[68:69], v[108:109], v[126:127] op_sel_hi:[0,1]
	v_pk_mul_f32 v[70:71], v[108:109], v[128:129] op_sel_hi:[0,1]
	v_pk_fma_f32 v[70:71], v[14:15], v[70:71], 0 op_sel_hi:[1,1,0]
	v_pk_fma_f32 v[68:69], v[12:13], v[68:69], 0 op_sel_hi:[1,1,0]
	global_store_dwordx4 v[72:73], v[64:67], off nt
	global_store_dwordx4 v[72:73], v[68:71], off offset:16 nt
	v_lshl_add_u64 v[72:73], s[0:1], 0, v[82:83]
	v_pk_mul_f32 v[64:65], v[108:109], v[130:131] op_sel_hi:[0,1]
	v_pk_mul_f32 v[66:67], v[108:109], v[132:133] op_sel_hi:[0,1]
	v_pk_fma_f32 v[66:67], v[6:7], v[66:67], 0 op_sel_hi:[1,1,0]
	v_pk_fma_f32 v[64:65], v[4:5], v[64:65], 0 op_sel_hi:[1,1,0]
	v_pk_mul_f32 v[68:69], v[108:109], v[134:135] op_sel_hi:[0,1]
	v_pk_mul_f32 v[70:71], v[108:109], v[136:137] op_sel_hi:[0,1]
	v_pk_fma_f32 v[70:71], v[2:3], v[70:71], 0 op_sel_hi:[1,1,0]
	v_pk_fma_f32 v[68:69], v[0:1], v[68:69], 0 op_sel_hi:[1,1,0]
	global_store_dwordx4 v[72:73], v[64:67], off nt
	global_store_dwordx4 v[72:73], v[68:71], off offset:16 nt
	s_nop 0
	v_lshlrev_b32_e32 v65, 16, v61
	v_lshlrev_b32_e32 v64, 16, v60
	v_and_b32_e32 v61, 0xffff0000, v61
	v_and_b32_e32 v60, 0xffff0000, v60
	v_pk_mul_f32 v[66:67], v[60:61], v[60:61]
	v_lshlrev_b32_e32 v69, 16, v63
	v_lshlrev_b32_e32 v68, 16, v62
	v_and_b32_e32 v63, 0xffff0000, v63
	v_and_b32_e32 v62, 0xffff0000, v62
	v_pk_fma_f32 v[66:67], v[64:65], v[64:65], v[66:67]
	v_pk_mul_f32 v[70:71], v[62:63], v[62:63]
	v_lshlrev_b32_e32 v114, 16, v48
	v_pk_fma_f32 v[70:71], v[68:69], v[68:69], v[70:71]
	v_lshlrev_b32_e32 v73, 16, v57
	v_lshlrev_b32_e32 v72, 16, v56
	v_and_b32_e32 v57, 0xffff0000, v57
	v_and_b32_e32 v56, 0xffff0000, v56
	v_and_b32_e32 v115, 0xffff0000, v48
	v_lshlrev_b32_e32 v116, 16, v49
	v_and_b32_e32 v117, 0xffff0000, v49
	v_lshlrev_b32_e32 v118, 16, v50
	v_and_b32_e32 v119, 0xffff0000, v50
	v_mul_f32_e32 v50, v114, v114
	v_pk_add_f32 v[48:49], v[66:67], v[66:67] op_sel:[0,1] op_sel_hi:[1,0]
	v_pk_mul_f32 v[74:75], v[56:57], v[56:57]
	v_lshlrev_b32_e32 v77, 16, v59
	v_lshlrev_b32_e32 v76, 16, v58
	v_and_b32_e32 v59, 0xffff0000, v59
	v_and_b32_e32 v58, 0xffff0000, v58
	v_lshlrev_b32_e32 v106, 16, v52
	v_and_b32_e32 v107, 0xffff0000, v52
	v_lshlrev_b32_e32 v120, 16, v51
	v_and_b32_e32 v121, 0xffff0000, v51
	v_mul_f32_e32 v52, v115, v115
	v_mov_b32_e32 v49, v50
	v_pk_add_f32 v[50:51], v[70:71], v[70:71] op_sel:[0,1] op_sel_hi:[1,0]
	v_pk_fma_f32 v[74:75], v[72:73], v[72:73], v[74:75]
	v_pk_mul_f32 v[78:79], v[58:59], v[58:59]
	v_mov_b32_e32 v51, v52
	v_pk_fma_f32 v[78:79], v[76:77], v[76:77], v[78:79]
	v_lshlrev_b32_e32 v108, 16, v53
	v_and_b32_e32 v109, 0xffff0000, v53
	v_mul_f32_e32 v53, v116, v116
	v_pk_add_f32 v[48:49], v[48:49], v[50:51]
	v_pk_add_f32 v[50:51], v[74:75], v[74:75] op_sel:[0,1] op_sel_hi:[1,0]
	v_lshlrev_b32_e32 v110, 16, v54
	v_and_b32_e32 v111, 0xffff0000, v54
	v_mul_f32_e32 v54, v117, v117
	v_mov_b32_e32 v51, v53
	v_pk_add_f32 v[52:53], v[78:79], v[78:79] op_sel:[0,1] op_sel_hi:[1,0]
	v_lshlrev_b32_e32 v112, 16, v55
	v_mov_b32_e32 v53, v54
	v_pk_add_f32 v[50:51], v[50:51], v[52:53]
	v_mul_f32_e32 v52, v109, v109
	v_pk_add_f32 v[48:49], v[48:49], v[50:51]
	v_mul_f32_e32 v50, v107, v107
	v_and_b32_e32 v113, 0xffff0000, v55
	v_mul_f32_e32 v55, v118, v118
	v_mul_f32_e32 v105, v119, v119
	v_pk_fma_f32 v[50:51], v[106:107], v[106:107], v[50:51] op_sel_hi:[1,1,0]
	v_pk_fma_f32 v[52:53], v[108:109], v[108:109], v[52:53] op_sel_hi:[1,1,0]
	v_mov_b32_e32 v51, v55
	v_mov_b32_e32 v53, v105
	v_pk_add_f32 v[50:51], v[50:51], v[52:53]
	v_mul_f32_e32 v52, v111, v111
	v_mul_f32_e32 v54, v113, v113
	v_mul_f32_e32 v122, v120, v120
	v_mul_f32_e32 v123, v121, v121
	v_pk_fma_f32 v[52:53], v[110:111], v[110:111], v[52:53] op_sel_hi:[1,1,0]
	v_pk_fma_f32 v[54:55], v[112:113], v[112:113], v[54:55] op_sel_hi:[1,1,0]
	v_mov_b32_e32 v53, v122
	v_mov_b32_e32 v55, v123
	v_pk_add_f32 v[52:53], v[52:53], v[54:55]
	s_nop 0
	v_pk_add_f32 v[50:51], v[50:51], v[52:53]
	s_nop 0
	v_pk_add_f32 v[48:49], v[48:49], v[50:51]
	s_nop 0
	v_add_f32_e32 v48, v48, v49
	ds_bpermute_b32 v49, v99, v48
	s_waitcnt lgkmcnt(0)
	v_add_f32_e32 v48, v48, v49
	ds_bpermute_b32 v49, v100, v48
	s_waitcnt lgkmcnt(0)
; #define GAS __attribute__((address_space(1)))
; __device__ __forceinline__ unsigned pk2(float lo, float hi) { return f2bf(lo) | (f2bf(hi) << 16); }
; #define NPR_LOAD(slot, row) do { _Pragma("unroll") for (int j = 0; j < 4; ++j) { const size_t o = (size_t)(row) * DM + 8 * (flane + 64 * j); \
;             if (P16) raw[P16 ? (slot) : 0][j] = *(const v4u*)(X16 + o); \
;             else { vf[P16 ? 0 : (slot)][j][0] = *(const f32x4*)(srcP32 + o); vf[P16 ? 0 : (slot)][j][1] = *(const f32x4*)(srcP32 + o + 4); } } } while (0)
; template <int OUTM, bool P16>
; __device__ __forceinline__ void norm_prompt_rows(Frame& F, const float* srcP32, const float* gain, int sub, bf16* Hd, float* yP) {
;     ...
;         for (int r = 0; r < 4; ++r) {
;             const int slot = r % RB;
;             float ss = 0.f;
; #pragma unroll
;             for (int j = 0; j < 4; ++j) { f32x4 x0, x1; NPR_GET(slot, j, x0, x1);
;                 ss += ((x0[0] * x0[0] + x0[1] * x0[1]) + (x0[2] * x0[2] + x0[3] * x0[3])) + ((x1[0] * x1[0] + x1[1] * x1[1]) + (x1[2] * x1[2] + x1[3] * x1[3])); }
;             const float rstd = 1.0f / sqrtf(wave_sum(ss) * (1.0f / DM) + EPS);
; #pragma unroll
;             for (int j = 0; j < 4; ++j) { const size_t o = (size_t)(m0 + r) * DM + 8 * (flane + 64 * j);
;                 f32x4 x0, x1; NPR_GET(slot, j, x0, x1);
;                 const f32x4 o0 = (x0 * rstd) * Am[j][0] + Bm[j][0], o1 = (x1 * rstd) * Am[j][1] + Bm[j][1];
;                 if (OUTM == 2) { __builtin_nontemporal_store(o0, (f32x4*)(yP + o)); __builtin_nontemporal_store(o1, (f32x4*)(yP + o + 4)); }
;                 else if (OUTM == 1) { v2u pk; pk.x = pg8::pk4_fp8(o0[0], o0[1], o0[2], o0[3]); pk.y = pg8::pk4_fp8(o1[0], o1[1], o1[2], o1[3]); *(GAS v2u*)((unsigned char*)Hd + o) = pk; }
;                 else { v4u pk; pk.x = pk2(o0[0], o0[1]); pk.y = pk2(o0[2], o0[3]); pk.z = pk2(o1[0], o1[1]); pk.w = pk2(o1[2], o1[3]); *(GAS v4u*)(Hd + o) = pk; } }
;             if (r + RB < 4) NPR_LOAD(slot, m0 + r + RB);
;             __builtin_amdgcn_sched_barrier(0);
;         }
	v_add_f32_e32 v48, v48, v49
	ds_bpermute_b32 v49, v101, v48
	s_waitcnt lgkmcnt(0)
	v_add_f32_e32 v48, v48, v49
	ds_bpermute_b32 v49, v102, v48
	s_waitcnt lgkmcnt(0)
	v_add_f32_e32 v48, v48, v49
	ds_bpermute_b32 v49, v103, v48
	s_waitcnt lgkmcnt(0)
	v_add_f32_e32 v48, v48, v49
	ds_bpermute_b32 v49, v104, v48
	s_waitcnt lgkmcnt(0)
	v_add_f32_e32 v48, v48, v49
	v_fmamk_f32 v48, v48, 0x3a000000, v97
	v_mul_f32_e32 v49, 0x4f800000, v48
	v_cmp_gt_f32_e32 vcc, s15, v48
	s_nop 1
	v_cndmask_b32_e32 v48, v48, v49, vcc
	v_sqrt_f32_e32 v49, v48
	s_nop 0
	v_add_u32_e32 v50, -1, v49
	v_fma_f32 v51, -v50, v49, v48
	v_cmp_ge_f32_e64 s[0:1], 0, v51
	v_add_u32_e32 v51, 1, v49
	s_nop 0
	v_cndmask_b32_e64 v50, v49, v50, s[0:1]
	v_fma_f32 v49, -v51, v49, v48
	v_cmp_lt_f32_e64 s[0:1], 0, v49
	s_nop 1
	v_cndmask_b32_e64 v49, v50, v51, s[0:1]
	v_mul_f32_e32 v50, 0x37800000, v49
	v_cndmask_b32_e32 v49, v49, v50, vcc
	v_cmp_class_f32_e32 vcc, v48, v98
	s_nop 1
	v_cndmask_b32_e32 v48, v49, v48, vcc
	v_div_scale_f32 v49, s[0:1], v48, v48, 1.0
	v_rcp_f32_e32 v50, v49
	s_lshl_b64 s[0:1], s[6:7], 13
	s_add_u32 s0, s76, s0
	s_addc_u32 s1, s77, s1
	v_fma_f32 v51, -v49, v50, 1.0
	v_fmac_f32_e32 v50, v51, v50
	v_div_scale_f32 v51, vcc, 1.0, v48, 1.0
	v_mul_f32_e32 v52, v51, v50
	v_fma_f32 v53, -v49, v52, v51
	v_fmac_f32_e32 v52, v53, v50
	v_fma_f32 v49, -v49, v52, v51
	v_div_fmas_f32 v49, v49, v50, v52
	v_div_fixup_f32 v66, v49, v48, 1.0
	v_mov_b32_e32 v48, v64
	v_mov_b32_e32 v49, v60
	v_mov_b32_e32 v60, v65
	v_pk_mul_f32 v[48:49], v[66:67], v[48:49] op_sel_hi:[0,1]
	v_pk_mul_f32 v[50:51], v[66:67], v[60:61] op_sel_hi:[0,1]
	v_mov_b32_e32 v52, v68
	v_mov_b32_e32 v53, v62
	v_mov_b32_e32 v62, v69
	v_pk_fma_f32 v[50:51], v[34:35], v[50:51], 0 op_sel_hi:[1,1,0]
	v_pk_fma_f32 v[48:49], v[32:33], v[48:49], 0 op_sel_hi:[1,1,0]
	v_pk_mul_f32 v[52:53], v[66:67], v[52:53] op_sel_hi:[0,1]
	v_pk_mul_f32 v[54:55], v[66:67], v[62:63] op_sel_hi:[0,1]
	v_lshl_add_u64 v[60:61], s[0:1], 0, v[80:81]
	v_pk_fma_f32 v[54:55], v[26:27], v[54:55], 0 op_sel_hi:[1,1,0]
	v_pk_fma_f32 v[52:53], v[24:25], v[52:53], 0 op_sel_hi:[1,1,0]
	global_store_dwordx4 v[60:61], v[48:51], off nt
	global_store_dwordx4 v[60:61], v[52:55], off offset:16 nt
	s_nop 0
	v_mov_b32_e32 v48, v72
	v_mov_b32_e32 v49, v56
	v_mov_b32_e32 v56, v73
	v_pk_mul_f32 v[48:49], v[66:67], v[48:49] op_sel_hi:[0,1]
	v_pk_mul_f32 v[50:51], v[66:67], v[56:57] op_sel_hi:[0,1]
	v_mov_b32_e32 v52, v76
	v_mov_b32_e32 v53, v58
	v_mov_b32_e32 v58, v77
	v_pk_fma_f32 v[50:51], v[18:19], v[50:51], 0 op_sel_hi:[1,1,0]
	v_pk_fma_f32 v[48:49], v[16:17], v[48:49], 0 op_sel_hi:[1,1,0]
	v_pk_mul_f32 v[52:53], v[66:67], v[52:53] op_sel_hi:[0,1]
	v_pk_mul_f32 v[54:55], v[66:67], v[58:59] op_sel_hi:[0,1]
	v_lshl_add_u64 v[56:57], s[0:1], 0, v[86:87]
	v_pk_fma_f32 v[54:55], v[10:11], v[54:55], 0 op_sel_hi:[1,1,0]
	v_pk_fma_f32 v[52:53], v[8:9], v[52:53], 0 op_sel_hi:[1,1,0]
	global_store_dwordx4 v[56:57], v[48:51], off nt
	global_store_dwordx4 v[56:57], v[52:55], off offset:16 nt
	v_lshl_add_u64 v[56:57], s[0:1], 0, v[84:85]
	v_pk_mul_f32 v[48:49], v[66:67], v[106:107] op_sel_hi:[0,1]
	v_pk_mul_f32 v[50:51], v[66:67], v[108:109] op_sel_hi:[0,1]
	v_pk_fma_f32 v[50:51], v[22:23], v[50:51], 0 op_sel_hi:[1,1,0]
	v_pk_fma_f32 v[48:49], v[20:21], v[48:49], 0 op_sel_hi:[1,1,0]
	v_pk_mul_f32 v[52:53], v[66:67], v[110:111] op_sel_hi:[0,1]
	v_pk_mul_f32 v[54:55], v[66:67], v[112:113] op_sel_hi:[0,1]
	v_pk_fma_f32 v[54:55], v[14:15], v[54:55], 0 op_sel_hi:[1,1,0]
	v_pk_fma_f32 v[52:53], v[12:13], v[52:53], 0 op_sel_hi:[1,1,0]
	global_store_dwordx4 v[56:57], v[48:51], off nt
	global_store_dwordx4 v[56:57], v[52:55], off offset:16 nt
	v_lshl_add_u64 v[56:57], s[0:1], 0, v[82:83]
	v_pk_mul_f32 v[48:49], v[66:67], v[114:115] op_sel_hi:[0,1]
	v_pk_mul_f32 v[50:51], v[66:67], v[116:117] op_sel_hi:[0,1]
	v_pk_fma_f32 v[50:51], v[6:7], v[50:51], 0 op_sel_hi:[1,1,0]
	v_pk_fma_f32 v[48:49], v[4:5], v[48:49], 0 op_sel_hi:[1,1,0]
	v_pk_mul_f32 v[52:53], v[66:67], v[118:119] op_sel_hi:[0,1]
	v_pk_mul_f32 v[54:55], v[66:67], v[120:121] op_sel_hi:[0,1]
	v_pk_fma_f32 v[54:55], v[2:3], v[54:55], 0 op_sel_hi:[1,1,0]
	v_pk_fma_f32 v[52:53], v[0:1], v[52:53], 0 op_sel_hi:[1,1,0]
	global_store_dwordx4 v[56:57], v[48:51], off nt
	global_store_dwordx4 v[56:57], v[52:55], off offset:16 nt
	s_nop 0
	v_lshlrev_b32_e32 v49, 16, v37
	v_lshlrev_b32_e32 v48, 16, v36
	v_and_b32_e32 v37, 0xffff0000, v37
	v_and_b32_e32 v36, 0xffff0000, v36
	v_lshlrev_b32_e32 v53, 16, v39
	v_lshlrev_b32_e32 v52, 16, v38
	v_and_b32_e32 v39, 0xffff0000, v39
	v_and_b32_e32 v38, 0xffff0000, v38
	v_and_b32_e32 v59, 0xffff0000, v29
	v_and_b32_e32 v58, 0xffff0000, v28
	v_and_b32_e32 v63, 0xffff0000, v31
	v_and_b32_e32 v62, 0xffff0000, v30
	v_pk_mul_f32 v[50:51], v[36:37], v[36:37]
	v_pk_mul_f32 v[54:55], v[38:39], v[38:39]
	v_lshlrev_b32_e32 v57, 16, v29
	v_lshlrev_b32_e32 v56, 16, v28
	v_pk_mul_f32 v[28:29], v[58:59], v[58:59]
	v_lshlrev_b32_e32 v61, 16, v31
	v_lshlrev_b32_e32 v60, 16, v30
	v_pk_mul_f32 v[30:31], v[62:63], v[62:63]
	v_pk_fma_f32 v[50:51], v[48:49], v[48:49], v[50:51]
	v_pk_fma_f32 v[54:55], v[52:53], v[52:53], v[54:55]
	v_pk_fma_f32 v[28:29], v[56:57], v[56:57], v[28:29]
	v_pk_fma_f32 v[30:31], v[60:61], v[60:61], v[30:31]
	v_lshlrev_b32_e32 v68, 16, v40
	v_and_b32_e32 v69, 0xffff0000, v40
	v_lshlrev_b32_e32 v40, 16, v41
	v_and_b32_e32 v41, 0xffff0000, v41
	v_mul_f32_e32 v72, v68, v68
	v_mul_f32_e32 v73, v69, v69
	v_mul_f32_e32 v74, v40, v40
	v_mul_f32_e32 v75, v41, v41
	v_pk_add_f32 v[50:51], v[50:51], v[50:51] op_sel:[0,1] op_sel_hi:[1,0]
	v_pk_add_f32 v[54:55], v[54:55], v[54:55] op_sel:[0,1] op_sel_hi:[1,0]
; template <int OUTM, bool P16>
; __device__ __forceinline__ void norm_prompt_rows(Frame& F, const float* srcP32, const float* gain, int sub, bf16* Hd, float* yP) {
;     ...
;     for (int mb = 32 * F.vcu; mb < MP; mb += 32 * F.G) {
;         const int m0 = mb + 4 * F.wave;
;         int flane = flane0; asm volatile("" : "+v"(flane));
;         v4u raw[P16 ? RB : 1][4]; f32x4 vf[P16 ? 1 : RB][4][2];
; #pragma unroll
;         for (int r = 0; r < RB; ++r) NPR_LOAD(r, m0 + r);
;         f32x4 Am[4][2], Bm[4][2];
;         if (OUTM == 2) {
; #pragma unroll
;             for (int j = 0; j < 4; ++j)
; #pragma unroll
;                 for (int hf = 0; hf < 2; ++hf) { Am[j][hf] = *(const f32x4*)(gain + 8 * (flane + 64 * j) + 4 * hf); Bm[j][hf] = (f32x4){0.f, 0.f, 0.f, 0.f}; }
;         } else {
;             { const int k = 4 * (64 * F.wave + flane);
;                 const float* sh = WSP(float, WS_MODS) + (size_t)pg8::modrow_of(mb) * NMOD + (size_t)(3 * sub) * DM; const float* sc = sh + DM;
;                 const f32x4 g4 = *(const f32x4*)(gain + k), s0 = *(const f32x4*)(sc + k), s1 = *(const f32x4*)(sc + MODSB_DELTA + k), h0 = *(const f32x4*)(sh + k), h1 = *(const f32x4*)(sh + MODSB_DELTA + k);
;                 *(LAS f32x4*)(modA + k) = g4 * ((s0 + s1) + 1.0f); *(LAS f32x4*)(modB + k) = h0 + h1; }
;             __syncthreads();
; #pragma unroll
;             for (int j = 0; j < 4; ++j)
; #pragma unroll
;                 for (int hf = 0; hf < 2; ++hf) { const int k = 8 * (flane + 64 * j) + 4 * hf; Am[j][hf] = *(const LAS f32x4*)(modA + k); Bm[j][hf] = *(const LAS f32x4*)(modB + k); }
;         }
; #pragma unroll
;         for (int r = 0; r < 4; ++r) {
;             const int slot = r % RB;
;             float ss = 0.f;
; #pragma unroll
;             for (int j = 0; j < 4; ++j) { f32x4 x0, x1; NPR_GET(slot, j, x0, x1);
;                 ss += ((x0[0] * x0[0] + x0[1] * x0[1]) + (x0[2] * x0[2] + x0[3] * x0[3])) + ((x1[0] * x1[0] + x1[1] * x1[1]) + (x1[2] * x1[2] + x1[3] * x1[3])); }
;             const float rstd = 1.0f / sqrtf(wave_sum(ss) * (1.0f / DM) + EPS);
; #pragma unroll
;             for (int j = 0; j < 4; ++j) { const size_t o = (size_t)(m0 + r) * DM + 8 * (flane + 64 * j);
;                 f32x4 x0, x1; NPR_GET(slot, j, x0, x1);
;                 const f32x4 o0 = (x0 * rstd) * Am[j][0] + Bm[j][0], o1 = (x1 * rstd) * Am[j][1] + Bm[j][1];
	v_pk_add_f32 v[28:29], v[28:29], v[28:29] op_sel:[0,1] op_sel_hi:[1,0]
	v_pk_add_f32 v[30:31], v[30:31], v[30:31] op_sel:[0,1] op_sel_hi:[1,0]
	v_mov_b32_e32 v51, v72
	v_mov_b32_e32 v55, v73
	v_mov_b32_e32 v29, v74
	v_mov_b32_e32 v31, v75
	v_lshlrev_b32_e32 v64, 16, v44
	v_and_b32_e32 v65, 0xffff0000, v44
	v_lshlrev_b32_e32 v44, 16, v45
	v_and_b32_e32 v45, 0xffff0000, v45
	v_pk_add_f32 v[50:51], v[50:51], v[54:55]
	v_pk_add_f32 v[28:29], v[28:29], v[30:31]
	v_lshlrev_b32_e32 v70, 16, v42
	v_and_b32_e32 v71, 0xffff0000, v42
	v_pk_add_f32 v[28:29], v[50:51], v[28:29]
	v_mul_f32_e32 v30, v65, v65
	v_mul_f32_e32 v50, v45, v45
	v_mul_f32_e32 v76, v70, v70
	v_mul_f32_e32 v77, v71, v71
	v_pk_fma_f32 v[30:31], v[64:65], v[64:65], v[30:31] op_sel_hi:[1,1,0]
	v_pk_fma_f32 v[50:51], v[44:45], v[44:45], v[50:51] op_sel_hi:[1,1,0]
	v_lshlrev_b32_e32 v66, 16, v46
	v_and_b32_e32 v67, 0xffff0000, v46
	v_lshlrev_b32_e32 v46, 16, v47
	v_and_b32_e32 v47, 0xffff0000, v47
	v_mov_b32_e32 v31, v76
	v_mov_b32_e32 v51, v77
	v_lshlrev_b32_e32 v42, 16, v43
	v_and_b32_e32 v43, 0xffff0000, v43
	v_pk_add_f32 v[30:31], v[30:31], v[50:51]
	v_mul_f32_e32 v50, v67, v67
	v_mul_f32_e32 v54, v47, v47
	v_mul_f32_e32 v78, v42, v42
	v_mul_f32_e32 v79, v43, v43
	v_pk_fma_f32 v[50:51], v[66:67], v[66:67], v[50:51] op_sel_hi:[1,1,0]
	v_pk_fma_f32 v[54:55], v[46:47], v[46:47], v[54:55] op_sel_hi:[1,1,0]
	v_mov_b32_e32 v51, v78
	v_mov_b32_e32 v55, v79
	v_pk_add_f32 v[50:51], v[50:51], v[54:55]
	s_nop 0
	v_pk_add_f32 v[30:31], v[30:31], v[50:51]
	s_nop 0
	v_pk_add_f32 v[28:29], v[28:29], v[30:31]
	s_nop 0
	v_add_f32_e32 v28, v28, v29
	ds_bpermute_b32 v29, v99, v28
	s_waitcnt lgkmcnt(0)
	v_add_f32_e32 v28, v28, v29
	ds_bpermute_b32 v29, v100, v28
	s_waitcnt lgkmcnt(0)
	v_add_f32_e32 v28, v28, v29
	ds_bpermute_b32 v29, v101, v28
	s_waitcnt lgkmcnt(0)
	v_add_f32_e32 v28, v28, v29
	ds_bpermute_b32 v29, v102, v28
	s_waitcnt lgkmcnt(0)
	v_add_f32_e32 v28, v28, v29
	ds_bpermute_b32 v29, v103, v28
	s_waitcnt lgkmcnt(0)
	v_add_f32_e32 v28, v28, v29
	ds_bpermute_b32 v29, v104, v28
	s_waitcnt lgkmcnt(0)
	v_add_f32_e32 v28, v28, v29
	v_fmamk_f32 v28, v28, 0x3a000000, v97
	v_mul_f32_e32 v29, 0x4f800000, v28
	v_cmp_gt_f32_e32 vcc, s15, v28
	s_nop 1
	v_cndmask_b32_e32 v28, v28, v29, vcc
	v_sqrt_f32_e32 v29, v28
	s_nop 0
	v_add_u32_e32 v30, -1, v29
	v_fma_f32 v31, -v30, v29, v28
	v_cmp_ge_f32_e64 s[0:1], 0, v31
	v_add_u32_e32 v31, 1, v29
	s_nop 0
	v_cndmask_b32_e64 v30, v29, v30, s[0:1]
	v_fma_f32 v29, -v31, v29, v28
	v_cmp_lt_f32_e64 s[0:1], 0, v29
	s_nop 1
	v_cndmask_b32_e64 v29, v30, v31, s[0:1]
	v_mul_f32_e32 v30, 0x37800000, v29
	v_cndmask_b32_e32 v29, v29, v30, vcc
	v_cmp_class_f32_e32 vcc, v28, v98
	s_nop 1
	v_cndmask_b32_e32 v28, v29, v28, vcc
	v_div_scale_f32 v29, s[0:1], v28, v28, 1.0
	v_rcp_f32_e32 v30, v29
	s_lshl_b64 s[0:1], s[2:3], 13
	s_add_u32 s0, s76, s0
	s_addc_u32 s1, s77, s1
	v_fma_f32 v31, -v29, v30, 1.0
	v_fmac_f32_e32 v30, v31, v30
	v_div_scale_f32 v31, vcc, 1.0, v28, 1.0
	v_mul_f32_e32 v50, v31, v30
	v_fma_f32 v51, -v29, v50, v31
	v_fmac_f32_e32 v50, v51, v30
	v_fma_f32 v29, -v29, v50, v31
	v_div_fmas_f32 v29, v29, v30, v50
	v_div_fixup_f32 v50, v29, v28, 1.0
	v_mov_b32_e32 v28, v48
	v_mov_b32_e32 v29, v36
	v_pk_mul_f32 v[28:29], v[50:51], v[28:29] op_sel_hi:[0,1]
	v_mov_b32_e32 v36, v49
	v_pk_fma_f32 v[28:29], v[32:33], v[28:29], 0 op_sel_hi:[1,1,0]
	v_mov_b32_e32 v32, v52
	v_mov_b32_e32 v33, v38
	v_pk_mul_f32 v[30:31], v[50:51], v[36:37] op_sel_hi:[0,1]
	v_pk_mul_f32 v[32:33], v[50:51], v[32:33] op_sel_hi:[0,1]
	v_mov_b32_e32 v38, v53
	v_pk_fma_f32 v[30:31], v[34:35], v[30:31], 0 op_sel_hi:[1,1,0]
	v_pk_mul_f32 v[34:35], v[50:51], v[38:39] op_sel_hi:[0,1]
	v_pk_fma_f32 v[24:25], v[24:25], v[32:33], 0 op_sel_hi:[1,1,0]
	v_lshl_add_u64 v[32:33], s[0:1], 0, v[80:81]
	v_pk_fma_f32 v[26:27], v[26:27], v[34:35], 0 op_sel_hi:[1,1,0]
	global_store_dwordx4 v[32:33], v[28:31], off nt
	global_store_dwordx4 v[32:33], v[24:27], off offset:16 nt
	s_nop 1
	v_mov_b32_e32 v24, v56
	v_mov_b32_e32 v25, v58
	v_pk_mul_f32 v[24:25], v[50:51], v[24:25] op_sel_hi:[0,1]
	v_mov_b32_e32 v58, v57
	v_pk_mul_f32 v[26:27], v[50:51], v[58:59] op_sel_hi:[0,1]
	v_pk_fma_f32 v[16:17], v[16:17], v[24:25], 0 op_sel_hi:[1,1,0]
	v_mov_b32_e32 v24, v60
	v_mov_b32_e32 v25, v62
	v_mov_b32_e32 v62, v61
	v_pk_fma_f32 v[18:19], v[18:19], v[26:27], 0 op_sel_hi:[1,1,0]
	v_pk_mul_f32 v[24:25], v[50:51], v[24:25] op_sel_hi:[0,1]
	v_pk_mul_f32 v[26:27], v[50:51], v[62:63] op_sel_hi:[0,1]
	v_pk_fma_f32 v[10:11], v[10:11], v[26:27], 0 op_sel_hi:[1,1,0]
	v_pk_fma_f32 v[8:9], v[8:9], v[24:25], 0 op_sel_hi:[1,1,0]
	v_lshl_add_u64 v[24:25], s[0:1], 0, v[86:87]
	global_store_dwordx4 v[24:25], v[16:19], off nt
	global_store_dwordx4 v[24:25], v[8:11], off offset:16 nt
	s_nop 0
	v_pk_mul_f32 v[16:17], v[50:51], v[66:67] op_sel_hi:[0,1]
	v_pk_mul_f32 v[8:9], v[50:51], v[64:65] op_sel_hi:[0,1]
	v_pk_mul_f32 v[10:11], v[50:51], v[44:45] op_sel_hi:[0,1]
	v_pk_fma_f32 v[10:11], v[22:23], v[10:11], 0 op_sel_hi:[1,1,0]
	v_pk_fma_f32 v[8:9], v[20:21], v[8:9], 0 op_sel_hi:[1,1,0]
	v_pk_mul_f32 v[18:19], v[50:51], v[46:47] op_sel_hi:[0,1]
	v_pk_fma_f32 v[12:13], v[12:13], v[16:17], 0 op_sel_hi:[1,1,0]
	v_lshl_add_u64 v[16:17], s[0:1], 0, v[84:85]
	v_pk_fma_f32 v[14:15], v[14:15], v[18:19], 0 op_sel_hi:[1,1,0]
	global_store_dwordx4 v[16:17], v[8:11], off nt
	global_store_dwordx4 v[16:17], v[12:15], off offset:16 nt
	s_nop 0
	v_pk_mul_f32 v[8:9], v[50:51], v[68:69] op_sel_hi:[0,1]
	v_pk_mul_f32 v[10:11], v[50:51], v[40:41] op_sel_hi:[0,1]
	v_pk_fma_f32 v[4:5], v[4:5], v[8:9], 0 op_sel_hi:[1,1,0]
	v_pk_mul_f32 v[8:9], v[50:51], v[70:71] op_sel_hi:[0,1]
	v_pk_fma_f32 v[6:7], v[6:7], v[10:11], 0 op_sel_hi:[1,1,0]
	v_pk_mul_f32 v[10:11], v[50:51], v[42:43] op_sel_hi:[0,1]
	v_pk_fma_f32 v[0:1], v[0:1], v[8:9], 0 op_sel_hi:[1,1,0]
	v_lshl_add_u64 v[8:9], s[0:1], 0, v[82:83]
	v_pk_fma_f32 v[2:3], v[2:3], v[10:11], 0 op_sel_hi:[1,1,0]
	global_store_dwordx4 v[8:9], v[4:7], off nt
	global_store_dwordx4 v[8:9], v[0:3], off offset:16 nt
	s_add_i32 s12, s12, s14
	s_cmpk_lt_i32 s12, 0x2000
	s_cbranch_scc1 .LBB0_1573
